# split-K sample-tile GEMMs: swapped MFMA operands so each f32 atomic instruction covers 4 full 64B row segments (was 16 quarter-used); same math
# speedup vs baseline: 1.0654x; 1.0654x over previous
.LBB0_2012:
	s_add_i32 s56, s88, s56
	s_and_b32 s57, s56, 7
	s_and_b32 s58, s42, 0xffffff00
	s_cmp_lt_i32 s56, 32
	s_cselect_b64 s[14:15], -1, 0
	s_and_b64 s[14:15], s[14:15], exec
	s_cselect_b32 s14, s58, s18
	s_ashr_i32 s15, s14, 31
	s_lshl_b64 s[16:17], s[14:15], 1
	s_lshl_b32 s14, s57, 20
	s_add_u32 s14, s3, s14
	s_addc_u32 s15, s4, 0
	s_add_u32 s14, s14, s16
	s_addc_u32 s15, s15, s17
	s_cmp_lt_i32 s56, 32
	s_cselect_b64 s[18:19], -1, 0
	ds_read_b128 v[18:21], v13
	ds_read_b128 v[22:25], v13 offset:1024
	ds_read_b128 v[26:29], v13 offset:2048
	ds_read_b128 v[30:33], v13 offset:3072
	s_and_b64 s[18:19], s[18:19], exec
	s_cselect_b32 s19, s15, s23
	s_cselect_b32 s18, s14, s22
	s_add_u32 s16, s27, s16
	s_addc_u32 s17, s29, s17
	s_cmp_lt_i32 s56, 32
	s_cselect_b64 s[24:25], -1, 0
	s_and_b64 vcc, s[24:25], exec
	s_cselect_b32 s25, s17, s21
	s_cselect_b32 s24, s16, s20
	s_add_u32 s60, s20, 0x80080
	s_addc_u32 s61, s21, 0
	s_mov_b32 m0, s44
	v_lshl_add_u64 v[68:69], s[60:61], 0, v[136:137]
	ds_read_b128 v[36:39], v14
	ds_read_b128 v[40:43], v14 offset:1024
	ds_read_b128 v[44:47], v14 offset:2048
	ds_read_b128 v[48:51], v14 offset:3072
	ds_read_b128 v[52:55], v14 offset:4096
	ds_read_b128 v[56:59], v14 offset:5120
	ds_read_b128 v[60:63], v14 offset:6144
	ds_read_b128 v[64:67], v14 offset:7168
	global_load_lds_dwordx4 v[68:69], off
	v_lshl_add_u64 v[68:69], s[60:61], 0, v[138:139]
	s_mov_b32 m0, s45
	s_nop 0
	global_load_lds_dwordx4 v[68:69], off
	s_waitcnt lgkmcnt(8)
	s_barrier
	s_waitcnt lgkmcnt(0)
	s_setprio 1
	s_waitcnt lgkmcnt(0)
	v_mfma_f32_16x16x32_bf16 v[68:71], v[36:39], v[18:21], 0
	v_mfma_f32_16x16x32_bf16 v[76:79], v[44:47], v[18:21], 0
	v_mfma_f32_16x16x32_bf16 v[84:87], v[52:55], v[18:21], 0
	v_mfma_f32_16x16x32_bf16 v[18:21], v[60:63], v[18:21], 0
	v_mfma_f32_16x16x32_bf16 v[68:71], v[40:43], v[22:25], v[68:71]
	v_mfma_f32_16x16x32_bf16 v[72:75], v[36:39], v[26:29], 0
	v_mfma_f32_16x16x32_bf16 v[76:79], v[48:51], v[22:25], v[76:79]
	v_mfma_f32_16x16x32_bf16 v[80:83], v[44:47], v[26:29], 0
	v_mfma_f32_16x16x32_bf16 v[84:87], v[56:59], v[22:25], v[84:87]
	v_mfma_f32_16x16x32_bf16 v[88:91], v[52:55], v[26:29], 0
	v_mfma_f32_16x16x32_bf16 v[18:21], v[64:67], v[22:25], v[18:21]
	v_mfma_f32_16x16x32_bf16 v[22:25], v[60:63], v[26:29], 0
	v_mfma_f32_16x16x32_bf16 v[72:75], v[40:43], v[30:33], v[72:75]
	v_mfma_f32_16x16x32_bf16 v[80:83], v[48:51], v[30:33], v[80:83]
	v_mfma_f32_16x16x32_bf16 v[88:91], v[56:59], v[30:33], v[88:91]
	v_mfma_f32_16x16x32_bf16 v[22:25], v[64:67], v[30:33], v[22:25]
	s_setprio 0
	s_barrier
	v_lshl_add_u64 v[132:133], s[22:23], 0, v[136:137]
	s_mov_b32 m0, s46
	v_lshl_add_u64 v[100:101], v[132:133], 0, s[10:11]
	v_lshl_add_u64 v[134:135], s[22:23], 0, v[138:139]
	ds_read_b128 v[26:29], v15
	ds_read_b128 v[30:33], v15 offset:1024
	ds_read_b128 v[92:95], v15 offset:2048
	ds_read_b128 v[96:99], v15 offset:3072
	global_load_lds_dwordx4 v[100:101], off
	v_lshl_add_u64 v[100:101], v[134:135], 0, s[10:11]
	s_mov_b32 m0, s47
	s_nop 0
	global_load_lds_dwordx4 v[100:101], off
	s_barrier
	s_waitcnt lgkmcnt(0)
	s_setprio 1
	s_waitcnt lgkmcnt(0)
	v_mfma_f32_16x16x32_bf16 v[100:103], v[36:39], v[26:29], 0
	v_mfma_f32_16x16x32_bf16 v[36:39], v[36:39], v[92:95], 0
	v_mfma_f32_16x16x32_bf16 v[100:103], v[40:43], v[30:33], v[100:103]
	v_mfma_f32_16x16x32_bf16 v[36:39], v[40:43], v[96:99], v[36:39]
	v_mfma_f32_16x16x32_bf16 v[40:43], v[44:47], v[26:29], 0
	v_mfma_f32_16x16x32_bf16 v[44:47], v[44:47], v[92:95], 0
	v_mfma_f32_16x16x32_bf16 v[40:43], v[48:51], v[30:33], v[40:43]
	v_mfma_f32_16x16x32_bf16 v[44:47], v[48:51], v[96:99], v[44:47]
	v_mfma_f32_16x16x32_bf16 v[48:51], v[52:55], v[26:29], 0
	v_mfma_f32_16x16x32_bf16 v[26:29], v[60:63], v[26:29], 0
	v_mfma_f32_16x16x32_bf16 v[48:51], v[56:59], v[30:33], v[48:51]
	v_mfma_f32_16x16x32_bf16 v[52:55], v[52:55], v[92:95], 0
	v_mfma_f32_16x16x32_bf16 v[26:29], v[64:67], v[30:33], v[26:29]
	v_mfma_f32_16x16x32_bf16 v[30:33], v[60:63], v[92:95], 0
	v_mfma_f32_16x16x32_bf16 v[52:55], v[56:59], v[96:99], v[52:55]
	v_mfma_f32_16x16x32_bf16 v[30:33], v[64:67], v[96:99], v[30:33]
	s_setprio 0
	v_lshl_add_u64 v[140:141], s[20:21], 0, v[136:137]
	s_mov_b32 m0, s26
	v_lshl_add_u64 v[56:57], v[140:141], 0, s[10:11]
	v_lshl_add_u64 v[142:143], s[20:21], 0, v[138:139]
	s_barrier
	global_load_lds_dwordx4 v[56:57], off
	v_lshl_add_u64 v[56:57], v[142:143], 0, s[10:11]
	s_mov_b32 m0, s30
	s_nop 0
	global_load_lds_dwordx4 v[56:57], off
	s_barrier
	s_waitcnt lgkmcnt(0)
	s_setprio 1
	s_setprio 0
	s_barrier
	s_add_u32 s60, s22, 0x80100
	s_addc_u32 s61, s23, 0
	s_mov_b32 m0, s48
	v_lshl_add_u64 v[56:57], s[60:61], 0, v[136:137]
	global_load_lds_dwordx4 v[56:57], off
	v_lshl_add_u64 v[56:57], s[60:61], 0, v[138:139]
	s_mov_b32 m0, s49
	s_nop 0
	global_load_lds_dwordx4 v[56:57], off
	s_waitcnt vmcnt(6)
	s_barrier
	s_setprio 1
	s_setprio 0
	s_barrier
	ds_read_b128 v[56:59], v16
	ds_read_b128 v[60:63], v16 offset:1024
	ds_read_b128 v[64:67], v16 offset:2048
	ds_read_b128 v[92:95], v16 offset:3072
	s_add_u32 s60, s20, 0x80100
	s_addc_u32 s61, s21, 0
	s_mov_b32 m0, s31
	v_lshl_add_u64 v[144:145], s[60:61], 0, v[136:137]
	ds_read_b128 v[96:99], v14 offset:32768
	ds_read_b128 v[104:107], v14 offset:33792
	ds_read_b128 v[108:111], v14 offset:34816
	ds_read_b128 v[112:115], v14 offset:35840
	ds_read_b128 v[116:119], v14 offset:36864
	ds_read_b128 v[120:123], v14 offset:37888
	ds_read_b128 v[124:127], v14 offset:38912
	ds_read_b128 v[128:131], v14 offset:39936
	global_load_lds_dwordx4 v[144:145], off
	v_lshl_add_u64 v[144:145], s[60:61], 0, v[138:139]
	s_mov_b32 m0, s33
	s_nop 0
	global_load_lds_dwordx4 v[144:145], off
	s_waitcnt lgkmcnt(8)
	s_barrier
	s_waitcnt lgkmcnt(0)
	s_setprio 1
	s_waitcnt lgkmcnt(0)
	v_mfma_f32_16x16x32_bf16 v[68:71], v[96:99], v[56:59], v[68:71]
	v_mfma_f32_16x16x32_bf16 v[72:75], v[96:99], v[64:67], v[72:75]
	v_mfma_f32_16x16x32_bf16 v[76:79], v[108:111], v[56:59], v[76:79]
	v_mfma_f32_16x16x32_bf16 v[80:83], v[108:111], v[64:67], v[80:83]
	v_mfma_f32_16x16x32_bf16 v[84:87], v[116:119], v[56:59], v[84:87]
	v_mfma_f32_16x16x32_bf16 v[88:91], v[116:119], v[64:67], v[88:91]
	v_mfma_f32_16x16x32_bf16 v[18:21], v[124:127], v[56:59], v[18:21]
	v_mfma_f32_16x16x32_bf16 v[22:25], v[124:127], v[64:67], v[22:25]
	v_mfma_f32_16x16x32_bf16 v[68:71], v[104:107], v[60:63], v[68:71]
	v_mfma_f32_16x16x32_bf16 v[72:75], v[104:107], v[92:95], v[72:75]
	v_mfma_f32_16x16x32_bf16 v[76:79], v[112:115], v[60:63], v[76:79]
	v_mfma_f32_16x16x32_bf16 v[80:83], v[112:115], v[92:95], v[80:83]
	v_mfma_f32_16x16x32_bf16 v[84:87], v[120:123], v[60:63], v[84:87]
	v_mfma_f32_16x16x32_bf16 v[88:91], v[120:123], v[92:95], v[88:91]
	v_mfma_f32_16x16x32_bf16 v[18:21], v[128:131], v[60:63], v[18:21]
	v_mfma_f32_16x16x32_bf16 v[22:25], v[128:131], v[92:95], v[22:25]
	s_setprio 0
	s_barrier
	s_mov_b32 m0, s52
	v_lshl_add_u64 v[132:133], v[132:133], 0, s[12:13]
	ds_read_b128 v[56:59], v17
	ds_read_b128 v[60:63], v17 offset:1024
	ds_read_b128 v[64:67], v17 offset:2048
	ds_read_b128 v[92:95], v17 offset:3072
	global_load_lds_dwordx4 v[132:133], off
	v_lshl_add_u64 v[132:133], v[134:135], 0, s[12:13]
	s_mov_b32 m0, s53
	s_nop 0
	global_load_lds_dwordx4 v[132:133], off
	s_barrier
	s_waitcnt lgkmcnt(0)
	s_setprio 1
	s_waitcnt lgkmcnt(0)
	v_mfma_f32_16x16x32_bf16 v[100:103], v[96:99], v[56:59], v[100:103]
	v_mfma_f32_16x16x32_bf16 v[36:39], v[96:99], v[64:67], v[36:39]
	v_mfma_f32_16x16x32_bf16 v[40:43], v[108:111], v[56:59], v[40:43]
	v_mfma_f32_16x16x32_bf16 v[44:47], v[108:111], v[64:67], v[44:47]
	v_mfma_f32_16x16x32_bf16 v[48:51], v[116:119], v[56:59], v[48:51]
	v_mfma_f32_16x16x32_bf16 v[52:55], v[116:119], v[64:67], v[52:55]
	v_mfma_f32_16x16x32_bf16 v[26:29], v[124:127], v[56:59], v[26:29]
	v_mfma_f32_16x16x32_bf16 v[30:33], v[124:127], v[64:67], v[30:33]
	v_mfma_f32_16x16x32_bf16 v[100:103], v[104:107], v[60:63], v[100:103]
	v_mfma_f32_16x16x32_bf16 v[36:39], v[104:107], v[92:95], v[36:39]
	v_mfma_f32_16x16x32_bf16 v[40:43], v[112:115], v[60:63], v[40:43]
	v_mfma_f32_16x16x32_bf16 v[44:47], v[112:115], v[92:95], v[44:47]
	v_mfma_f32_16x16x32_bf16 v[48:51], v[120:123], v[60:63], v[48:51]
	v_mfma_f32_16x16x32_bf16 v[52:55], v[120:123], v[92:95], v[52:55]
	v_mfma_f32_16x16x32_bf16 v[26:29], v[128:131], v[60:63], v[26:29]
	v_mfma_f32_16x16x32_bf16 v[30:33], v[128:131], v[92:95], v[30:33]
	s_setprio 0
	s_mov_b32 m0, s40
	v_lshl_add_u64 v[56:57], v[140:141], 0, s[12:13]
	s_barrier
	global_load_lds_dwordx4 v[56:57], off
	v_lshl_add_u64 v[56:57], v[142:143], 0, s[12:13]
	s_mov_b32 m0, s41
	s_nop 0
	global_load_lds_dwordx4 v[56:57], off
	s_barrier
	s_waitcnt lgkmcnt(0)
	s_setprio 1
	s_setprio 0
	s_barrier
	s_add_u32 s22, s22, 0x80180
	s_addc_u32 s23, s23, 0
	s_mov_b32 m0, s54
	v_lshl_add_u64 v[56:57], s[22:23], 0, v[136:137]
	global_load_lds_dwordx4 v[56:57], off
	v_lshl_add_u64 v[56:57], s[22:23], 0, v[138:139]
	s_mov_b32 m0, s55
	s_nop 0
	global_load_lds_dwordx4 v[56:57], off
	s_waitcnt vmcnt(6)
	s_barrier
	s_setprio 1
	s_setprio 0
	s_barrier
	ds_read_b128 v[56:59], v13
	ds_read_b128 v[60:63], v13 offset:1024
	ds_read_b128 v[64:67], v13 offset:2048
	ds_read_b128 v[92:95], v13 offset:3072
	s_add_u32 s20, s20, 0x80180
	s_addc_u32 s21, s21, 0
	s_mov_b32 m0, s44
	v_lshl_add_u64 v[132:133], s[20:21], 0, v[136:137]
	ds_read_b128 v[96:99], v14
	ds_read_b128 v[104:107], v14 offset:1024
	ds_read_b128 v[108:111], v14 offset:2048
	ds_read_b128 v[112:115], v14 offset:3072
	ds_read_b128 v[116:119], v14 offset:4096
	ds_read_b128 v[120:123], v14 offset:5120
	ds_read_b128 v[124:127], v14 offset:6144
	ds_read_b128 v[128:131], v14 offset:7168
	global_load_lds_dwordx4 v[132:133], off
	v_lshl_add_u64 v[132:133], s[20:21], 0, v[138:139]
	s_mov_b32 m0, s45
	s_nop 0
	global_load_lds_dwordx4 v[132:133], off
	s_waitcnt lgkmcnt(8)
	s_barrier
	s_waitcnt lgkmcnt(0)
	s_setprio 1
	s_waitcnt lgkmcnt(0)
	v_mfma_f32_16x16x32_bf16 v[68:71], v[96:99], v[56:59], v[68:71]
	v_mfma_f32_16x16x32_bf16 v[72:75], v[96:99], v[64:67], v[72:75]
	v_mfma_f32_16x16x32_bf16 v[76:79], v[108:111], v[56:59], v[76:79]
	v_mfma_f32_16x16x32_bf16 v[80:83], v[108:111], v[64:67], v[80:83]
	v_mfma_f32_16x16x32_bf16 v[84:87], v[116:119], v[56:59], v[84:87]
	v_mfma_f32_16x16x32_bf16 v[88:91], v[116:119], v[64:67], v[88:91]
	v_mfma_f32_16x16x32_bf16 v[18:21], v[124:127], v[56:59], v[18:21]
	v_mfma_f32_16x16x32_bf16 v[22:25], v[124:127], v[64:67], v[22:25]
	v_mfma_f32_16x16x32_bf16 v[68:71], v[104:107], v[60:63], v[68:71]
	v_mfma_f32_16x16x32_bf16 v[72:75], v[104:107], v[92:95], v[72:75]
	v_mfma_f32_16x16x32_bf16 v[76:79], v[112:115], v[60:63], v[76:79]
	v_mfma_f32_16x16x32_bf16 v[80:83], v[112:115], v[92:95], v[80:83]
	v_mfma_f32_16x16x32_bf16 v[84:87], v[120:123], v[60:63], v[84:87]
	v_mfma_f32_16x16x32_bf16 v[88:91], v[120:123], v[92:95], v[88:91]
	v_mfma_f32_16x16x32_bf16 v[18:21], v[128:131], v[60:63], v[18:21]
	v_mfma_f32_16x16x32_bf16 v[22:25], v[128:131], v[92:95], v[22:25]
	s_setprio 0
	s_barrier
	s_mov_b32 m0, s46
	v_lshl_add_u64 v[132:133], s[18:19], 0, v[136:137]
	ds_read_b128 v[56:59], v15
	ds_read_b128 v[60:63], v15 offset:1024
	ds_read_b128 v[64:67], v15 offset:2048
	ds_read_b128 v[92:95], v15 offset:3072
	global_load_lds_dwordx4 v[132:133], off
	v_lshl_add_u64 v[134:135], s[18:19], 0, v[138:139]
	s_mov_b32 m0, s47
	s_nop 0
	global_load_lds_dwordx4 v[134:135], off
	s_barrier
	s_waitcnt lgkmcnt(0)
	s_setprio 1
	s_waitcnt lgkmcnt(0)
	v_mfma_f32_16x16x32_bf16 v[100:103], v[96:99], v[56:59], v[100:103]
	v_mfma_f32_16x16x32_bf16 v[36:39], v[96:99], v[64:67], v[36:39]
	v_mfma_f32_16x16x32_bf16 v[40:43], v[108:111], v[56:59], v[40:43]
	v_mfma_f32_16x16x32_bf16 v[44:47], v[108:111], v[64:67], v[44:47]
	v_mfma_f32_16x16x32_bf16 v[48:51], v[116:119], v[56:59], v[48:51]
	v_mfma_f32_16x16x32_bf16 v[52:55], v[116:119], v[64:67], v[52:55]
	v_mfma_f32_16x16x32_bf16 v[26:29], v[124:127], v[56:59], v[26:29]
	v_mfma_f32_16x16x32_bf16 v[30:33], v[124:127], v[64:67], v[30:33]
	v_mfma_f32_16x16x32_bf16 v[100:103], v[104:107], v[60:63], v[100:103]
	v_mfma_f32_16x16x32_bf16 v[36:39], v[104:107], v[92:95], v[36:39]
	v_mfma_f32_16x16x32_bf16 v[40:43], v[112:115], v[60:63], v[40:43]
	v_mfma_f32_16x16x32_bf16 v[44:47], v[112:115], v[92:95], v[44:47]
	v_mfma_f32_16x16x32_bf16 v[48:51], v[120:123], v[60:63], v[48:51]
	v_mfma_f32_16x16x32_bf16 v[52:55], v[120:123], v[92:95], v[52:55]
	v_mfma_f32_16x16x32_bf16 v[26:29], v[128:131], v[60:63], v[26:29]
	v_mfma_f32_16x16x32_bf16 v[30:33], v[128:131], v[92:95], v[30:33]
	s_setprio 0
	s_mov_b32 m0, s26
	v_lshl_add_u64 v[140:141], s[24:25], 0, v[136:137]
	s_barrier
	global_load_lds_dwordx4 v[140:141], off
	v_lshl_add_u64 v[142:143], s[24:25], 0, v[138:139]
	s_mov_b32 m0, s30
	s_nop 0
	global_load_lds_dwordx4 v[142:143], off
	s_barrier
	s_waitcnt lgkmcnt(0)
	s_setprio 1
	s_setprio 0
	s_barrier
	s_add_u32 s20, s18, 0x80000
	s_addc_u32 s21, s19, 0
	s_mov_b32 m0, s48
	v_lshl_add_u64 v[56:57], s[20:21], 0, v[136:137]
	global_load_lds_dwordx4 v[56:57], off
	v_lshl_add_u64 v[56:57], s[20:21], 0, v[138:139]
	s_mov_b32 m0, s49
	s_nop 0
	global_load_lds_dwordx4 v[56:57], off
	s_waitcnt vmcnt(6)
	s_barrier
	s_setprio 1
	s_setprio 0
	s_barrier
	ds_read_b128 v[56:59], v16
	ds_read_b128 v[60:63], v16 offset:1024
	ds_read_b128 v[64:67], v16 offset:2048
	ds_read_b128 v[92:95], v16 offset:3072
	s_add_u32 s20, s24, 0x80000
	s_addc_u32 s21, s25, 0
	s_mov_b32 m0, s31
	v_lshl_add_u64 v[144:145], s[20:21], 0, v[136:137]
	ds_read_b128 v[96:99], v14 offset:32768
	ds_read_b128 v[104:107], v14 offset:33792
	ds_read_b128 v[108:111], v14 offset:34816
	ds_read_b128 v[112:115], v14 offset:35840
	ds_read_b128 v[116:119], v14 offset:36864
	ds_read_b128 v[120:123], v14 offset:37888
	ds_read_b128 v[124:127], v14 offset:38912
	ds_read_b128 v[128:131], v14 offset:39936
	global_load_lds_dwordx4 v[144:145], off
	v_lshl_add_u64 v[144:145], s[20:21], 0, v[138:139]
	s_mov_b32 m0, s33
	s_nop 0
	global_load_lds_dwordx4 v[144:145], off
	s_waitcnt lgkmcnt(8)
	s_barrier
	s_waitcnt lgkmcnt(0)
	s_setprio 1
	s_waitcnt lgkmcnt(0)
	v_mfma_f32_16x16x32_bf16 v[68:71], v[96:99], v[56:59], v[68:71]
	v_mfma_f32_16x16x32_bf16 v[72:75], v[96:99], v[64:67], v[72:75]
	v_mfma_f32_16x16x32_bf16 v[76:79], v[108:111], v[56:59], v[76:79]
	v_mfma_f32_16x16x32_bf16 v[80:83], v[108:111], v[64:67], v[80:83]
	v_mfma_f32_16x16x32_bf16 v[84:87], v[116:119], v[56:59], v[84:87]
	v_mfma_f32_16x16x32_bf16 v[88:91], v[116:119], v[64:67], v[88:91]
	v_mfma_f32_16x16x32_bf16 v[18:21], v[124:127], v[56:59], v[18:21]
	v_mfma_f32_16x16x32_bf16 v[22:25], v[124:127], v[64:67], v[22:25]
	v_mfma_f32_16x16x32_bf16 v[68:71], v[104:107], v[60:63], v[68:71]
	v_mfma_f32_16x16x32_bf16 v[72:75], v[104:107], v[92:95], v[72:75]
	v_mfma_f32_16x16x32_bf16 v[76:79], v[112:115], v[60:63], v[76:79]
	v_mfma_f32_16x16x32_bf16 v[80:83], v[112:115], v[92:95], v[80:83]
	v_mfma_f32_16x16x32_bf16 v[84:87], v[120:123], v[60:63], v[84:87]
	v_mfma_f32_16x16x32_bf16 v[88:91], v[120:123], v[92:95], v[88:91]
	v_mfma_f32_16x16x32_bf16 v[18:21], v[128:131], v[60:63], v[18:21]
	v_mfma_f32_16x16x32_bf16 v[22:25], v[128:131], v[92:95], v[22:25]
	s_setprio 0
	s_barrier
	s_mov_b32 m0, s52
	v_lshl_add_u64 v[132:133], v[132:133], 0, s[8:9]
	ds_read_b128 v[56:59], v17
	ds_read_b128 v[60:63], v17 offset:1024
	ds_read_b128 v[64:67], v17 offset:2048
	ds_read_b128 v[92:95], v17 offset:3072
	global_load_lds_dwordx4 v[132:133], off
	v_lshl_add_u64 v[132:133], v[134:135], 0, s[8:9]
	s_mov_b32 m0, s53
	s_nop 0
	global_load_lds_dwordx4 v[132:133], off
	s_barrier
	s_waitcnt lgkmcnt(0)
	s_setprio 1
	s_waitcnt lgkmcnt(0)
	v_mfma_f32_16x16x32_bf16 v[100:103], v[96:99], v[56:59], v[100:103]
	v_mfma_f32_16x16x32_bf16 v[36:39], v[96:99], v[64:67], v[36:39]
	v_mfma_f32_16x16x32_bf16 v[40:43], v[108:111], v[56:59], v[40:43]
	v_mfma_f32_16x16x32_bf16 v[44:47], v[108:111], v[64:67], v[44:47]
	v_mfma_f32_16x16x32_bf16 v[48:51], v[116:119], v[56:59], v[48:51]
	v_mfma_f32_16x16x32_bf16 v[52:55], v[116:119], v[64:67], v[52:55]
	v_mfma_f32_16x16x32_bf16 v[26:29], v[124:127], v[56:59], v[26:29]
	v_mfma_f32_16x16x32_bf16 v[30:33], v[124:127], v[64:67], v[30:33]
	v_mfma_f32_16x16x32_bf16 v[100:103], v[104:107], v[60:63], v[100:103]
	v_mfma_f32_16x16x32_bf16 v[36:39], v[104:107], v[92:95], v[36:39]
	v_mfma_f32_16x16x32_bf16 v[40:43], v[112:115], v[60:63], v[40:43]
	v_mfma_f32_16x16x32_bf16 v[44:47], v[112:115], v[92:95], v[44:47]
	v_mfma_f32_16x16x32_bf16 v[48:51], v[120:123], v[60:63], v[48:51]
	v_mfma_f32_16x16x32_bf16 v[52:55], v[120:123], v[92:95], v[52:55]
	v_mfma_f32_16x16x32_bf16 v[26:29], v[128:131], v[60:63], v[26:29]
	v_mfma_f32_16x16x32_bf16 v[30:33], v[128:131], v[92:95], v[30:33]
	s_setprio 0
	s_mov_b32 m0, s40
	v_lshl_add_u64 v[56:57], v[140:141], 0, s[8:9]
	s_barrier
	global_load_lds_dwordx4 v[56:57], off
	v_lshl_add_u64 v[56:57], v[142:143], 0, s[8:9]
	s_mov_b32 m0, s41
	s_nop 0
	global_load_lds_dwordx4 v[56:57], off
	s_barrier
	s_waitcnt lgkmcnt(0)
	s_setprio 1
	s_setprio 0
	s_barrier
	s_add_u32 s18, s18, 0x80080
	s_addc_u32 s19, s19, 0
	s_mov_b32 m0, s54
	v_lshl_add_u64 v[56:57], s[18:19], 0, v[136:137]
	global_load_lds_dwordx4 v[56:57], off
	v_lshl_add_u64 v[56:57], s[18:19], 0, v[138:139]
	s_mov_b32 m0, s55
	s_nop 0
	global_load_lds_dwordx4 v[56:57], off
	s_waitcnt vmcnt(6)
	s_barrier
	s_setprio 1
	s_setprio 0
	v_lshl_or_b32 v2, s59, 8, v12
	v_lshlrev_b64 v[56:57], 2, v[2:3]
	v_lshl_add_u64 v[58:59], v[4:5], 0, v[56:57]
	s_barrier
	s_mov_b64 s[98:99], 0x2000
	s_mov_b64 s[100:101], 0x1a000
	v_mbcnt_lo_u32_b32 v60, -1, 0
	v_mbcnt_hi_u32_b32 v60, -1, v60
	v_and_b32_e32 v61, 15, v60
	v_lshrrev_b32_e32 v60, 4, v60
	v_lshlrev_b32_e32 v60, 2, v60
	v_sub_u32_e32 v60, v60, v61
	v_mul_i32_i24_e32 v60, 0x1ffc, v60
	v_ashrrev_i32_e32 v61, 31, v60
	v_lshl_add_u64 v[58:59], v[60:61], 0, v[58:59]
	global_atomic_add_f32 v[58:59], v68, off
	global_atomic_add_f32 v[58:59], v72, off offset:64
	global_atomic_add_f32 v[58:59], v100, off offset:512
	global_atomic_add_f32 v[58:59], v36, off offset:576
	v_lshl_add_u64 v[60:61], v[58:59], 0, s[98:99]
	global_atomic_add_f32 v[60:61], v69, off
	global_atomic_add_f32 v[60:61], v73, off offset:64
	global_atomic_add_f32 v[60:61], v101, off offset:512
	global_atomic_add_f32 v[60:61], v37, off offset:576
	v_lshl_add_u64 v[58:59], v[60:61], 0, s[98:99]
	global_atomic_add_f32 v[58:59], v70, off
	global_atomic_add_f32 v[58:59], v74, off offset:64
	global_atomic_add_f32 v[58:59], v102, off offset:512
	global_atomic_add_f32 v[58:59], v38, off offset:576
	v_lshl_add_u64 v[60:61], v[58:59], 0, s[98:99]
	global_atomic_add_f32 v[60:61], v71, off
	global_atomic_add_f32 v[60:61], v75, off offset:64
	global_atomic_add_f32 v[60:61], v103, off offset:512
	global_atomic_add_f32 v[60:61], v39, off offset:576
	v_lshl_add_u64 v[58:59], v[60:61], 0, s[100:101]
	global_atomic_add_f32 v[58:59], v76, off
	global_atomic_add_f32 v[58:59], v80, off offset:64
	global_atomic_add_f32 v[58:59], v40, off offset:512
	global_atomic_add_f32 v[58:59], v44, off offset:576
	v_lshl_add_u64 v[60:61], v[58:59], 0, s[98:99]
	global_atomic_add_f32 v[60:61], v77, off
	global_atomic_add_f32 v[60:61], v81, off offset:64
	global_atomic_add_f32 v[60:61], v41, off offset:512
	global_atomic_add_f32 v[60:61], v45, off offset:576
	v_lshl_add_u64 v[58:59], v[60:61], 0, s[98:99]
	global_atomic_add_f32 v[58:59], v78, off
	global_atomic_add_f32 v[58:59], v82, off offset:64
	global_atomic_add_f32 v[58:59], v42, off offset:512
	global_atomic_add_f32 v[58:59], v46, off offset:576
	v_lshl_add_u64 v[60:61], v[58:59], 0, s[98:99]
	global_atomic_add_f32 v[60:61], v79, off
	global_atomic_add_f32 v[60:61], v83, off offset:64
	global_atomic_add_f32 v[60:61], v43, off offset:512
	global_atomic_add_f32 v[60:61], v47, off offset:576
	v_lshl_add_u64 v[58:59], v[60:61], 0, s[100:101]
	global_atomic_add_f32 v[58:59], v84, off
	global_atomic_add_f32 v[58:59], v88, off offset:64
	global_atomic_add_f32 v[58:59], v48, off offset:512
	global_atomic_add_f32 v[58:59], v52, off offset:576
	v_lshl_add_u64 v[60:61], v[58:59], 0, s[98:99]
	global_atomic_add_f32 v[60:61], v85, off
	global_atomic_add_f32 v[60:61], v89, off offset:64
	global_atomic_add_f32 v[60:61], v49, off offset:512
	global_atomic_add_f32 v[60:61], v53, off offset:576
	v_lshl_add_u64 v[58:59], v[60:61], 0, s[98:99]
	global_atomic_add_f32 v[58:59], v86, off
	global_atomic_add_f32 v[58:59], v90, off offset:64
	global_atomic_add_f32 v[58:59], v50, off offset:512
	global_atomic_add_f32 v[58:59], v54, off offset:576
	v_lshl_add_u64 v[60:61], v[58:59], 0, s[98:99]
	global_atomic_add_f32 v[60:61], v87, off
	global_atomic_add_f32 v[60:61], v91, off offset:64
	global_atomic_add_f32 v[60:61], v51, off offset:512
	global_atomic_add_f32 v[60:61], v55, off offset:576
	v_lshl_add_u64 v[58:59], v[60:61], 0, s[100:101]
	global_atomic_add_f32 v[58:59], v18, off
	global_atomic_add_f32 v[58:59], v22, off offset:64
	global_atomic_add_f32 v[58:59], v26, off offset:512
	global_atomic_add_f32 v[58:59], v30, off offset:576
	v_lshl_add_u64 v[60:61], v[58:59], 0, s[98:99]
	global_atomic_add_f32 v[60:61], v19, off
	global_atomic_add_f32 v[60:61], v23, off offset:64
	global_atomic_add_f32 v[60:61], v27, off offset:512
	global_atomic_add_f32 v[60:61], v31, off offset:576
	v_lshl_add_u64 v[58:59], v[60:61], 0, s[98:99]
	global_atomic_add_f32 v[58:59], v20, off
	global_atomic_add_f32 v[58:59], v24, off offset:64
	global_atomic_add_f32 v[58:59], v28, off offset:512
	global_atomic_add_f32 v[58:59], v32, off offset:576
	v_lshl_add_u64 v[60:61], v[58:59], 0, s[98:99]
	global_atomic_add_f32 v[60:61], v21, off
	global_atomic_add_f32 v[60:61], v25, off offset:64
	global_atomic_add_f32 v[60:61], v29, off offset:512
	global_atomic_add_f32 v[60:61], v33, off offset:576
	s_add_i32 s42, s42, s43
	s_mov_b32 s59, s57
	s_mov_b32 s18, s58
	s_mov_b64 s[22:23], s[14:15]
	s_mov_b64 s[20:21], s[16:17]
	s_cbranch_vccnz .LBB0_2012
	s_waitcnt vmcnt(0)
	s_cmpk_gt_u32 s2, 0xff
	s_cbranch_scc1 .LBB0_2015
	s_barrier

.LBB0_2020:
	s_add_i32 s54, s88, s54
	s_and_b32 s56, s40, 0xffffff00
	s_and_b32 s55, s54, 7
	s_addk_i32 s56, 0x400
	s_cmp_lt_i32 s54, 32
	s_cselect_b64 s[12:13], -1, 0
	s_and_b64 s[12:13], s[12:13], exec
	s_cselect_b32 s12, s56, s16
	s_ashr_i32 s13, s12, 31
	s_lshl_b64 s[14:15], s[12:13], 1
	s_lshl_b32 s12, s55, 20
	s_add_u32 s12, s3, s12
	s_addc_u32 s13, s4, 0
	s_add_u32 s12, s12, s14
	s_addc_u32 s13, s13, s15
	s_cmp_lt_i32 s54, 32
	s_cselect_b64 s[16:17], -1, 0
	ds_read_b128 v[18:21], v13
	ds_read_b128 v[22:25], v13 offset:1024
	ds_read_b128 v[26:29], v13 offset:2048
	ds_read_b128 v[30:33], v13 offset:3072
	s_and_b64 s[16:17], s[16:17], exec
	s_cselect_b32 s17, s13, s21
	s_cselect_b32 s16, s12, s20
	s_add_u32 s14, s25, s14
	s_addc_u32 s15, s26, s15
	s_cmp_lt_i32 s54, 32
	s_cselect_b64 s[22:23], -1, 0
	s_and_b64 vcc, s[22:23], exec
	s_cselect_b32 s23, s15, s19
	s_cselect_b32 s22, s14, s18
	s_add_u32 s58, s18, 0x80080
	s_addc_u32 s59, s19, 0
	s_mov_b32 m0, s42
	v_lshl_add_u64 v[68:69], s[58:59], 0, v[136:137]
	ds_read_b128 v[36:39], v14
	ds_read_b128 v[40:43], v14 offset:1024
	ds_read_b128 v[44:47], v14 offset:2048
	ds_read_b128 v[48:51], v14 offset:3072
	ds_read_b128 v[52:55], v14 offset:4096
	ds_read_b128 v[56:59], v14 offset:5120
	ds_read_b128 v[60:63], v14 offset:6144
	ds_read_b128 v[64:67], v14 offset:7168
	global_load_lds_dwordx4 v[68:69], off
	v_lshl_add_u64 v[68:69], s[58:59], 0, v[138:139]
	s_mov_b32 m0, s43
	s_nop 0
	global_load_lds_dwordx4 v[68:69], off
	s_waitcnt lgkmcnt(8)
	s_barrier
	s_waitcnt lgkmcnt(0)
	s_setprio 1
	s_waitcnt lgkmcnt(0)
	v_mfma_f32_16x16x32_bf16 v[68:71], v[36:39], v[18:21], 0
	v_mfma_f32_16x16x32_bf16 v[76:79], v[44:47], v[18:21], 0
	v_mfma_f32_16x16x32_bf16 v[84:87], v[52:55], v[18:21], 0
	v_mfma_f32_16x16x32_bf16 v[18:21], v[60:63], v[18:21], 0
	v_mfma_f32_16x16x32_bf16 v[68:71], v[40:43], v[22:25], v[68:71]
	v_mfma_f32_16x16x32_bf16 v[72:75], v[36:39], v[26:29], 0
	v_mfma_f32_16x16x32_bf16 v[76:79], v[48:51], v[22:25], v[76:79]
	v_mfma_f32_16x16x32_bf16 v[80:83], v[44:47], v[26:29], 0
	v_mfma_f32_16x16x32_bf16 v[84:87], v[56:59], v[22:25], v[84:87]
	v_mfma_f32_16x16x32_bf16 v[88:91], v[52:55], v[26:29], 0
	v_mfma_f32_16x16x32_bf16 v[18:21], v[64:67], v[22:25], v[18:21]
	v_mfma_f32_16x16x32_bf16 v[22:25], v[60:63], v[26:29], 0
	v_mfma_f32_16x16x32_bf16 v[72:75], v[40:43], v[30:33], v[72:75]
	v_mfma_f32_16x16x32_bf16 v[80:83], v[48:51], v[30:33], v[80:83]
	v_mfma_f32_16x16x32_bf16 v[88:91], v[56:59], v[30:33], v[88:91]
	v_mfma_f32_16x16x32_bf16 v[22:25], v[64:67], v[30:33], v[22:25]
	s_setprio 0
	s_barrier
	v_lshl_add_u64 v[132:133], s[20:21], 0, v[136:137]
	s_mov_b32 m0, s44
	v_lshl_add_u64 v[100:101], v[132:133], 0, s[8:9]
	v_lshl_add_u64 v[134:135], s[20:21], 0, v[138:139]
	ds_read_b128 v[26:29], v15
	ds_read_b128 v[30:33], v15 offset:1024
	ds_read_b128 v[92:95], v15 offset:2048
	ds_read_b128 v[96:99], v15 offset:3072
	global_load_lds_dwordx4 v[100:101], off
	v_lshl_add_u64 v[100:101], v[134:135], 0, s[8:9]
	s_mov_b32 m0, s45
	s_nop 0
	global_load_lds_dwordx4 v[100:101], off
	s_barrier
	s_waitcnt lgkmcnt(0)
	s_setprio 1
	s_waitcnt lgkmcnt(0)
	v_mfma_f32_16x16x32_bf16 v[100:103], v[36:39], v[26:29], 0
	v_mfma_f32_16x16x32_bf16 v[36:39], v[36:39], v[92:95], 0
	v_mfma_f32_16x16x32_bf16 v[100:103], v[40:43], v[30:33], v[100:103]
	v_mfma_f32_16x16x32_bf16 v[36:39], v[40:43], v[96:99], v[36:39]
	v_mfma_f32_16x16x32_bf16 v[40:43], v[44:47], v[26:29], 0
	v_mfma_f32_16x16x32_bf16 v[44:47], v[44:47], v[92:95], 0
	v_mfma_f32_16x16x32_bf16 v[40:43], v[48:51], v[30:33], v[40:43]
	v_mfma_f32_16x16x32_bf16 v[44:47], v[48:51], v[96:99], v[44:47]
	v_mfma_f32_16x16x32_bf16 v[48:51], v[52:55], v[26:29], 0
	v_mfma_f32_16x16x32_bf16 v[26:29], v[60:63], v[26:29], 0
	v_mfma_f32_16x16x32_bf16 v[48:51], v[56:59], v[30:33], v[48:51]
	v_mfma_f32_16x16x32_bf16 v[52:55], v[52:55], v[92:95], 0
	v_mfma_f32_16x16x32_bf16 v[26:29], v[64:67], v[30:33], v[26:29]
	v_mfma_f32_16x16x32_bf16 v[30:33], v[60:63], v[92:95], 0
	v_mfma_f32_16x16x32_bf16 v[52:55], v[56:59], v[96:99], v[52:55]
	v_mfma_f32_16x16x32_bf16 v[30:33], v[64:67], v[96:99], v[30:33]
	s_setprio 0
	v_lshl_add_u64 v[140:141], s[18:19], 0, v[136:137]
	s_mov_b32 m0, s24
	v_lshl_add_u64 v[56:57], v[140:141], 0, s[8:9]
	v_lshl_add_u64 v[142:143], s[18:19], 0, v[138:139]
	s_barrier
	global_load_lds_dwordx4 v[56:57], off
	v_lshl_add_u64 v[56:57], v[142:143], 0, s[8:9]
	s_mov_b32 m0, s27
	s_nop 0
	global_load_lds_dwordx4 v[56:57], off
	s_barrier
	s_waitcnt lgkmcnt(0)
	s_setprio 1
	s_setprio 0
	s_barrier
	s_add_u32 s58, s20, 0x80100
	s_addc_u32 s59, s21, 0
	s_mov_b32 m0, s46
	v_lshl_add_u64 v[56:57], s[58:59], 0, v[136:137]
	global_load_lds_dwordx4 v[56:57], off
	v_lshl_add_u64 v[56:57], s[58:59], 0, v[138:139]
	s_mov_b32 m0, s47
	s_nop 0
	global_load_lds_dwordx4 v[56:57], off
	s_waitcnt vmcnt(6)
	s_barrier
	s_setprio 1
	s_setprio 0
	s_barrier
	ds_read_b128 v[56:59], v16
	ds_read_b128 v[60:63], v16 offset:1024
	ds_read_b128 v[64:67], v16 offset:2048
	ds_read_b128 v[92:95], v16 offset:3072
	s_add_u32 s58, s18, 0x80100
	s_addc_u32 s59, s19, 0
	s_mov_b32 m0, s29
	v_lshl_add_u64 v[144:145], s[58:59], 0, v[136:137]
	ds_read_b128 v[96:99], v14 offset:32768
	ds_read_b128 v[104:107], v14 offset:33792
	ds_read_b128 v[108:111], v14 offset:34816
	ds_read_b128 v[112:115], v14 offset:35840
	ds_read_b128 v[116:119], v14 offset:36864
	ds_read_b128 v[120:123], v14 offset:37888
	ds_read_b128 v[124:127], v14 offset:38912
	ds_read_b128 v[128:131], v14 offset:39936
	global_load_lds_dwordx4 v[144:145], off
	v_lshl_add_u64 v[144:145], s[58:59], 0, v[138:139]
	s_mov_b32 m0, s30
	s_nop 0
	global_load_lds_dwordx4 v[144:145], off
	s_waitcnt lgkmcnt(8)
	s_barrier
	s_waitcnt lgkmcnt(0)
	s_setprio 1
	s_waitcnt lgkmcnt(0)
	v_mfma_f32_16x16x32_bf16 v[68:71], v[96:99], v[56:59], v[68:71]
	v_mfma_f32_16x16x32_bf16 v[72:75], v[96:99], v[64:67], v[72:75]
	v_mfma_f32_16x16x32_bf16 v[76:79], v[108:111], v[56:59], v[76:79]
	v_mfma_f32_16x16x32_bf16 v[80:83], v[108:111], v[64:67], v[80:83]
	v_mfma_f32_16x16x32_bf16 v[84:87], v[116:119], v[56:59], v[84:87]
	v_mfma_f32_16x16x32_bf16 v[88:91], v[116:119], v[64:67], v[88:91]
	v_mfma_f32_16x16x32_bf16 v[18:21], v[124:127], v[56:59], v[18:21]
	v_mfma_f32_16x16x32_bf16 v[22:25], v[124:127], v[64:67], v[22:25]
	v_mfma_f32_16x16x32_bf16 v[68:71], v[104:107], v[60:63], v[68:71]
	v_mfma_f32_16x16x32_bf16 v[72:75], v[104:107], v[92:95], v[72:75]
	v_mfma_f32_16x16x32_bf16 v[76:79], v[112:115], v[60:63], v[76:79]
	v_mfma_f32_16x16x32_bf16 v[80:83], v[112:115], v[92:95], v[80:83]
	v_mfma_f32_16x16x32_bf16 v[84:87], v[120:123], v[60:63], v[84:87]
	v_mfma_f32_16x16x32_bf16 v[88:91], v[120:123], v[92:95], v[88:91]
	v_mfma_f32_16x16x32_bf16 v[18:21], v[128:131], v[60:63], v[18:21]
	v_mfma_f32_16x16x32_bf16 v[22:25], v[128:131], v[92:95], v[22:25]
	s_setprio 0
	s_barrier
	s_mov_b32 m0, s48
	v_lshl_add_u64 v[132:133], v[132:133], 0, s[10:11]
	ds_read_b128 v[56:59], v17
	ds_read_b128 v[60:63], v17 offset:1024
	ds_read_b128 v[64:67], v17 offset:2048
	ds_read_b128 v[92:95], v17 offset:3072
	global_load_lds_dwordx4 v[132:133], off
	v_lshl_add_u64 v[132:133], v[134:135], 0, s[10:11]
	s_mov_b32 m0, s49
	s_nop 0
	global_load_lds_dwordx4 v[132:133], off
	s_barrier
	s_waitcnt lgkmcnt(0)
	s_setprio 1
	s_waitcnt lgkmcnt(0)
	v_mfma_f32_16x16x32_bf16 v[100:103], v[96:99], v[56:59], v[100:103]
	v_mfma_f32_16x16x32_bf16 v[36:39], v[96:99], v[64:67], v[36:39]
	v_mfma_f32_16x16x32_bf16 v[40:43], v[108:111], v[56:59], v[40:43]
	v_mfma_f32_16x16x32_bf16 v[44:47], v[108:111], v[64:67], v[44:47]
	v_mfma_f32_16x16x32_bf16 v[48:51], v[116:119], v[56:59], v[48:51]
	v_mfma_f32_16x16x32_bf16 v[52:55], v[116:119], v[64:67], v[52:55]
	v_mfma_f32_16x16x32_bf16 v[26:29], v[124:127], v[56:59], v[26:29]
	v_mfma_f32_16x16x32_bf16 v[30:33], v[124:127], v[64:67], v[30:33]
	v_mfma_f32_16x16x32_bf16 v[100:103], v[104:107], v[60:63], v[100:103]
	v_mfma_f32_16x16x32_bf16 v[36:39], v[104:107], v[92:95], v[36:39]
	v_mfma_f32_16x16x32_bf16 v[40:43], v[112:115], v[60:63], v[40:43]
	v_mfma_f32_16x16x32_bf16 v[44:47], v[112:115], v[92:95], v[44:47]
	v_mfma_f32_16x16x32_bf16 v[48:51], v[120:123], v[60:63], v[48:51]
	v_mfma_f32_16x16x32_bf16 v[52:55], v[120:123], v[92:95], v[52:55]
	v_mfma_f32_16x16x32_bf16 v[26:29], v[128:131], v[60:63], v[26:29]
	v_mfma_f32_16x16x32_bf16 v[30:33], v[128:131], v[92:95], v[30:33]
	s_setprio 0
	s_mov_b32 m0, s31
	v_lshl_add_u64 v[56:57], v[140:141], 0, s[10:11]
	s_barrier
	global_load_lds_dwordx4 v[56:57], off
	v_lshl_add_u64 v[56:57], v[142:143], 0, s[10:11]
	s_mov_b32 m0, s33
	s_nop 0
	global_load_lds_dwordx4 v[56:57], off
	s_barrier
	s_waitcnt lgkmcnt(0)
	s_setprio 1
	s_setprio 0
	s_barrier
	s_add_u32 s20, s20, 0x80180
	s_addc_u32 s21, s21, 0
	s_mov_b32 m0, s52
	v_lshl_add_u64 v[56:57], s[20:21], 0, v[136:137]
	global_load_lds_dwordx4 v[56:57], off
	v_lshl_add_u64 v[56:57], s[20:21], 0, v[138:139]
	s_mov_b32 m0, s53
	s_nop 0
	global_load_lds_dwordx4 v[56:57], off
	s_waitcnt vmcnt(6)
	s_barrier
	s_setprio 1
	s_setprio 0
	s_barrier
	ds_read_b128 v[56:59], v13
	ds_read_b128 v[60:63], v13 offset:1024
	ds_read_b128 v[64:67], v13 offset:2048
	ds_read_b128 v[92:95], v13 offset:3072
	s_add_u32 s18, s18, 0x80180
	s_addc_u32 s19, s19, 0
	s_mov_b32 m0, s42
	v_lshl_add_u64 v[132:133], s[18:19], 0, v[136:137]
	ds_read_b128 v[96:99], v14
	ds_read_b128 v[104:107], v14 offset:1024
	ds_read_b128 v[108:111], v14 offset:2048
	ds_read_b128 v[112:115], v14 offset:3072
	ds_read_b128 v[116:119], v14 offset:4096
	ds_read_b128 v[120:123], v14 offset:5120
	ds_read_b128 v[124:127], v14 offset:6144
	ds_read_b128 v[128:131], v14 offset:7168
	global_load_lds_dwordx4 v[132:133], off
	v_lshl_add_u64 v[132:133], s[18:19], 0, v[138:139]
	s_mov_b32 m0, s43
	s_nop 0
	global_load_lds_dwordx4 v[132:133], off
	s_waitcnt lgkmcnt(8)
	s_barrier
	s_waitcnt lgkmcnt(0)
	s_setprio 1
	s_waitcnt lgkmcnt(0)
	v_mfma_f32_16x16x32_bf16 v[68:71], v[96:99], v[56:59], v[68:71]
	v_mfma_f32_16x16x32_bf16 v[72:75], v[96:99], v[64:67], v[72:75]
	v_mfma_f32_16x16x32_bf16 v[76:79], v[108:111], v[56:59], v[76:79]
	v_mfma_f32_16x16x32_bf16 v[80:83], v[108:111], v[64:67], v[80:83]
	v_mfma_f32_16x16x32_bf16 v[84:87], v[116:119], v[56:59], v[84:87]
	v_mfma_f32_16x16x32_bf16 v[88:91], v[116:119], v[64:67], v[88:91]
	v_mfma_f32_16x16x32_bf16 v[18:21], v[124:127], v[56:59], v[18:21]
	v_mfma_f32_16x16x32_bf16 v[22:25], v[124:127], v[64:67], v[22:25]
	v_mfma_f32_16x16x32_bf16 v[68:71], v[104:107], v[60:63], v[68:71]
	v_mfma_f32_16x16x32_bf16 v[72:75], v[104:107], v[92:95], v[72:75]
	v_mfma_f32_16x16x32_bf16 v[76:79], v[112:115], v[60:63], v[76:79]
	v_mfma_f32_16x16x32_bf16 v[80:83], v[112:115], v[92:95], v[80:83]
	v_mfma_f32_16x16x32_bf16 v[84:87], v[120:123], v[60:63], v[84:87]
	v_mfma_f32_16x16x32_bf16 v[88:91], v[120:123], v[92:95], v[88:91]
	v_mfma_f32_16x16x32_bf16 v[18:21], v[128:131], v[60:63], v[18:21]
	v_mfma_f32_16x16x32_bf16 v[22:25], v[128:131], v[92:95], v[22:25]
	s_setprio 0
	s_barrier
	s_mov_b32 m0, s44
	v_lshl_add_u64 v[132:133], s[16:17], 0, v[136:137]
	ds_read_b128 v[56:59], v15
	ds_read_b128 v[60:63], v15 offset:1024
	ds_read_b128 v[64:67], v15 offset:2048
	ds_read_b128 v[92:95], v15 offset:3072
	global_load_lds_dwordx4 v[132:133], off
	v_lshl_add_u64 v[134:135], s[16:17], 0, v[138:139]
	s_mov_b32 m0, s45
	s_nop 0
	global_load_lds_dwordx4 v[134:135], off
	s_barrier
	s_waitcnt lgkmcnt(0)
	s_setprio 1
	s_waitcnt lgkmcnt(0)
	v_mfma_f32_16x16x32_bf16 v[100:103], v[96:99], v[56:59], v[100:103]
	v_mfma_f32_16x16x32_bf16 v[36:39], v[96:99], v[64:67], v[36:39]
	v_mfma_f32_16x16x32_bf16 v[40:43], v[108:111], v[56:59], v[40:43]
	v_mfma_f32_16x16x32_bf16 v[44:47], v[108:111], v[64:67], v[44:47]
	v_mfma_f32_16x16x32_bf16 v[48:51], v[116:119], v[56:59], v[48:51]
	v_mfma_f32_16x16x32_bf16 v[52:55], v[116:119], v[64:67], v[52:55]
	v_mfma_f32_16x16x32_bf16 v[26:29], v[124:127], v[56:59], v[26:29]
	v_mfma_f32_16x16x32_bf16 v[30:33], v[124:127], v[64:67], v[30:33]
	v_mfma_f32_16x16x32_bf16 v[100:103], v[104:107], v[60:63], v[100:103]
	v_mfma_f32_16x16x32_bf16 v[36:39], v[104:107], v[92:95], v[36:39]
	v_mfma_f32_16x16x32_bf16 v[40:43], v[112:115], v[60:63], v[40:43]
	v_mfma_f32_16x16x32_bf16 v[44:47], v[112:115], v[92:95], v[44:47]
	v_mfma_f32_16x16x32_bf16 v[48:51], v[120:123], v[60:63], v[48:51]
	v_mfma_f32_16x16x32_bf16 v[52:55], v[120:123], v[92:95], v[52:55]
	v_mfma_f32_16x16x32_bf16 v[26:29], v[128:131], v[60:63], v[26:29]
	v_mfma_f32_16x16x32_bf16 v[30:33], v[128:131], v[92:95], v[30:33]
	s_setprio 0
	s_mov_b32 m0, s24
	v_lshl_add_u64 v[140:141], s[22:23], 0, v[136:137]
	s_barrier
	global_load_lds_dwordx4 v[140:141], off
	v_lshl_add_u64 v[142:143], s[22:23], 0, v[138:139]
	s_mov_b32 m0, s27
	s_nop 0
	global_load_lds_dwordx4 v[142:143], off
	s_barrier
	s_waitcnt lgkmcnt(0)
	s_setprio 1
	s_setprio 0
	s_barrier
	s_add_u32 s18, s16, 0x80000
	s_addc_u32 s19, s17, 0
	s_mov_b32 m0, s46
	v_lshl_add_u64 v[56:57], s[18:19], 0, v[136:137]
	global_load_lds_dwordx4 v[56:57], off
	v_lshl_add_u64 v[56:57], s[18:19], 0, v[138:139]
	s_mov_b32 m0, s47
	s_nop 0
	global_load_lds_dwordx4 v[56:57], off
	s_waitcnt vmcnt(6)
	s_barrier
	s_setprio 1
	s_setprio 0
	s_barrier
	ds_read_b128 v[56:59], v16
	ds_read_b128 v[60:63], v16 offset:1024
	ds_read_b128 v[64:67], v16 offset:2048
	ds_read_b128 v[92:95], v16 offset:3072
	s_add_u32 s18, s22, 0x80000
	s_addc_u32 s19, s23, 0
	s_mov_b32 m0, s29
	v_lshl_add_u64 v[144:145], s[18:19], 0, v[136:137]
	ds_read_b128 v[96:99], v14 offset:32768
	ds_read_b128 v[104:107], v14 offset:33792
	ds_read_b128 v[108:111], v14 offset:34816
	ds_read_b128 v[112:115], v14 offset:35840
	ds_read_b128 v[116:119], v14 offset:36864
	ds_read_b128 v[120:123], v14 offset:37888
	ds_read_b128 v[124:127], v14 offset:38912
	ds_read_b128 v[128:131], v14 offset:39936
	global_load_lds_dwordx4 v[144:145], off
	v_lshl_add_u64 v[144:145], s[18:19], 0, v[138:139]
	s_mov_b32 m0, s30
	s_nop 0
	global_load_lds_dwordx4 v[144:145], off
	s_waitcnt lgkmcnt(8)
	s_barrier
	s_waitcnt lgkmcnt(0)
	s_setprio 1
	s_waitcnt lgkmcnt(0)
	v_mfma_f32_16x16x32_bf16 v[68:71], v[96:99], v[56:59], v[68:71]
	v_mfma_f32_16x16x32_bf16 v[72:75], v[96:99], v[64:67], v[72:75]
	v_mfma_f32_16x16x32_bf16 v[76:79], v[108:111], v[56:59], v[76:79]
	v_mfma_f32_16x16x32_bf16 v[80:83], v[108:111], v[64:67], v[80:83]
	v_mfma_f32_16x16x32_bf16 v[84:87], v[116:119], v[56:59], v[84:87]
	v_mfma_f32_16x16x32_bf16 v[88:91], v[116:119], v[64:67], v[88:91]
	v_mfma_f32_16x16x32_bf16 v[18:21], v[124:127], v[56:59], v[18:21]
	v_mfma_f32_16x16x32_bf16 v[22:25], v[124:127], v[64:67], v[22:25]
	v_mfma_f32_16x16x32_bf16 v[68:71], v[104:107], v[60:63], v[68:71]
	v_mfma_f32_16x16x32_bf16 v[72:75], v[104:107], v[92:95], v[72:75]
	v_mfma_f32_16x16x32_bf16 v[76:79], v[112:115], v[60:63], v[76:79]
	v_mfma_f32_16x16x32_bf16 v[80:83], v[112:115], v[92:95], v[80:83]
	v_mfma_f32_16x16x32_bf16 v[84:87], v[120:123], v[60:63], v[84:87]
	v_mfma_f32_16x16x32_bf16 v[88:91], v[120:123], v[92:95], v[88:91]
	v_mfma_f32_16x16x32_bf16 v[18:21], v[128:131], v[60:63], v[18:21]
	v_mfma_f32_16x16x32_bf16 v[22:25], v[128:131], v[92:95], v[22:25]
	s_setprio 0
	s_barrier
	s_mov_b32 m0, s48
	v_lshl_add_u64 v[132:133], v[132:133], 0, s[0:1]
	ds_read_b128 v[56:59], v17
	ds_read_b128 v[60:63], v17 offset:1024
	ds_read_b128 v[64:67], v17 offset:2048
	ds_read_b128 v[92:95], v17 offset:3072
	global_load_lds_dwordx4 v[132:133], off
	v_lshl_add_u64 v[132:133], v[134:135], 0, s[0:1]
	s_mov_b32 m0, s49
	s_nop 0
	global_load_lds_dwordx4 v[132:133], off
	s_barrier
	s_waitcnt lgkmcnt(0)
	s_setprio 1
	s_waitcnt lgkmcnt(0)
	v_mfma_f32_16x16x32_bf16 v[100:103], v[96:99], v[56:59], v[100:103]
	v_mfma_f32_16x16x32_bf16 v[36:39], v[96:99], v[64:67], v[36:39]
	v_mfma_f32_16x16x32_bf16 v[40:43], v[108:111], v[56:59], v[40:43]
	v_mfma_f32_16x16x32_bf16 v[44:47], v[108:111], v[64:67], v[44:47]
	v_mfma_f32_16x16x32_bf16 v[48:51], v[116:119], v[56:59], v[48:51]
	v_mfma_f32_16x16x32_bf16 v[52:55], v[116:119], v[64:67], v[52:55]
	v_mfma_f32_16x16x32_bf16 v[26:29], v[124:127], v[56:59], v[26:29]
	v_mfma_f32_16x16x32_bf16 v[30:33], v[124:127], v[64:67], v[30:33]
	v_mfma_f32_16x16x32_bf16 v[100:103], v[104:107], v[60:63], v[100:103]
	v_mfma_f32_16x16x32_bf16 v[36:39], v[104:107], v[92:95], v[36:39]
	v_mfma_f32_16x16x32_bf16 v[40:43], v[112:115], v[60:63], v[40:43]
	v_mfma_f32_16x16x32_bf16 v[44:47], v[112:115], v[92:95], v[44:47]
	v_mfma_f32_16x16x32_bf16 v[48:51], v[120:123], v[60:63], v[48:51]
	v_mfma_f32_16x16x32_bf16 v[52:55], v[120:123], v[92:95], v[52:55]
	v_mfma_f32_16x16x32_bf16 v[26:29], v[128:131], v[60:63], v[26:29]
	v_mfma_f32_16x16x32_bf16 v[30:33], v[128:131], v[92:95], v[30:33]
	s_setprio 0
	s_mov_b32 m0, s31
	v_lshl_add_u64 v[56:57], v[140:141], 0, s[0:1]
	s_barrier
	global_load_lds_dwordx4 v[56:57], off
	v_lshl_add_u64 v[56:57], v[142:143], 0, s[0:1]
	s_mov_b32 m0, s33
	s_nop 0
	global_load_lds_dwordx4 v[56:57], off
	s_barrier
	s_waitcnt lgkmcnt(0)
	s_setprio 1
	s_setprio 0
	s_barrier
	s_add_u32 s16, s16, 0x80080
	s_addc_u32 s17, s17, 0
	s_mov_b32 m0, s52
	v_lshl_add_u64 v[56:57], s[16:17], 0, v[136:137]
	global_load_lds_dwordx4 v[56:57], off
	v_lshl_add_u64 v[56:57], s[16:17], 0, v[138:139]
	s_mov_b32 m0, s53
	s_nop 0
	global_load_lds_dwordx4 v[56:57], off
	s_waitcnt vmcnt(6)
	s_barrier
	s_setprio 1
	s_setprio 0
	v_lshl_or_b32 v2, s5, 8, v12
	v_lshlrev_b64 v[56:57], 2, v[2:3]
	v_lshl_add_u64 v[58:59], v[4:5], 0, v[56:57]
	s_barrier
	s_mov_b64 s[98:99], 0x2000
	s_mov_b64 s[100:101], 0x1a000
	v_mbcnt_lo_u32_b32 v60, -1, 0
	v_mbcnt_hi_u32_b32 v60, -1, v60
	v_and_b32_e32 v61, 15, v60
	v_lshrrev_b32_e32 v60, 4, v60
	v_lshlrev_b32_e32 v60, 2, v60
	v_sub_u32_e32 v60, v60, v61
	v_mul_i32_i24_e32 v60, 0x1ffc, v60
	v_ashrrev_i32_e32 v61, 31, v60
	v_lshl_add_u64 v[58:59], v[60:61], 0, v[58:59]
	global_atomic_add_f32 v[58:59], v68, off
	global_atomic_add_f32 v[58:59], v72, off offset:64
	global_atomic_add_f32 v[58:59], v100, off offset:512
	global_atomic_add_f32 v[58:59], v36, off offset:576
	v_lshl_add_u64 v[60:61], v[58:59], 0, s[98:99]
	global_atomic_add_f32 v[60:61], v69, off
	global_atomic_add_f32 v[60:61], v73, off offset:64
	global_atomic_add_f32 v[60:61], v101, off offset:512
	global_atomic_add_f32 v[60:61], v37, off offset:576
	v_lshl_add_u64 v[58:59], v[60:61], 0, s[98:99]
	global_atomic_add_f32 v[58:59], v70, off
	global_atomic_add_f32 v[58:59], v74, off offset:64
	global_atomic_add_f32 v[58:59], v102, off offset:512
	global_atomic_add_f32 v[58:59], v38, off offset:576
	v_lshl_add_u64 v[60:61], v[58:59], 0, s[98:99]
	global_atomic_add_f32 v[60:61], v71, off
	global_atomic_add_f32 v[60:61], v75, off offset:64
	global_atomic_add_f32 v[60:61], v103, off offset:512
	global_atomic_add_f32 v[60:61], v39, off offset:576
	v_lshl_add_u64 v[58:59], v[60:61], 0, s[100:101]
	global_atomic_add_f32 v[58:59], v76, off
	global_atomic_add_f32 v[58:59], v80, off offset:64
	global_atomic_add_f32 v[58:59], v40, off offset:512
	global_atomic_add_f32 v[58:59], v44, off offset:576
	v_lshl_add_u64 v[60:61], v[58:59], 0, s[98:99]
	global_atomic_add_f32 v[60:61], v77, off
	global_atomic_add_f32 v[60:61], v81, off offset:64
	global_atomic_add_f32 v[60:61], v41, off offset:512
	global_atomic_add_f32 v[60:61], v45, off offset:576
	v_lshl_add_u64 v[58:59], v[60:61], 0, s[98:99]
	global_atomic_add_f32 v[58:59], v78, off
	global_atomic_add_f32 v[58:59], v82, off offset:64
	global_atomic_add_f32 v[58:59], v42, off offset:512
	global_atomic_add_f32 v[58:59], v46, off offset:576
	v_lshl_add_u64 v[60:61], v[58:59], 0, s[98:99]
	global_atomic_add_f32 v[60:61], v79, off
	global_atomic_add_f32 v[60:61], v83, off offset:64
	global_atomic_add_f32 v[60:61], v43, off offset:512
	global_atomic_add_f32 v[60:61], v47, off offset:576
	v_lshl_add_u64 v[58:59], v[60:61], 0, s[100:101]
	global_atomic_add_f32 v[58:59], v84, off
	global_atomic_add_f32 v[58:59], v88, off offset:64
	global_atomic_add_f32 v[58:59], v48, off offset:512
	global_atomic_add_f32 v[58:59], v52, off offset:576
	v_lshl_add_u64 v[60:61], v[58:59], 0, s[98:99]
	global_atomic_add_f32 v[60:61], v85, off
	global_atomic_add_f32 v[60:61], v89, off offset:64
	global_atomic_add_f32 v[60:61], v49, off offset:512
	global_atomic_add_f32 v[60:61], v53, off offset:576
	v_lshl_add_u64 v[58:59], v[60:61], 0, s[98:99]
	global_atomic_add_f32 v[58:59], v86, off
	global_atomic_add_f32 v[58:59], v90, off offset:64
	global_atomic_add_f32 v[58:59], v50, off offset:512
	global_atomic_add_f32 v[58:59], v54, off offset:576
	v_lshl_add_u64 v[60:61], v[58:59], 0, s[98:99]
	global_atomic_add_f32 v[60:61], v87, off
	global_atomic_add_f32 v[60:61], v91, off offset:64
	global_atomic_add_f32 v[60:61], v51, off offset:512
	global_atomic_add_f32 v[60:61], v55, off offset:576
	v_lshl_add_u64 v[58:59], v[60:61], 0, s[100:101]
	global_atomic_add_f32 v[58:59], v18, off
	global_atomic_add_f32 v[58:59], v22, off offset:64
	global_atomic_add_f32 v[58:59], v26, off offset:512
	global_atomic_add_f32 v[58:59], v30, off offset:576
	v_lshl_add_u64 v[60:61], v[58:59], 0, s[98:99]
	global_atomic_add_f32 v[60:61], v19, off
	global_atomic_add_f32 v[60:61], v23, off offset:64
	global_atomic_add_f32 v[60:61], v27, off offset:512
	global_atomic_add_f32 v[60:61], v31, off offset:576
	v_lshl_add_u64 v[58:59], v[60:61], 0, s[98:99]
	global_atomic_add_f32 v[58:59], v20, off
	global_atomic_add_f32 v[58:59], v24, off offset:64
	global_atomic_add_f32 v[58:59], v28, off offset:512
	global_atomic_add_f32 v[58:59], v32, off offset:576
	v_lshl_add_u64 v[60:61], v[58:59], 0, s[98:99]
	global_atomic_add_f32 v[60:61], v21, off
	global_atomic_add_f32 v[60:61], v25, off offset:64
	global_atomic_add_f32 v[60:61], v29, off offset:512
	global_atomic_add_f32 v[60:61], v33, off offset:576
	s_add_i32 s40, s40, s41
	s_mov_b32 s5, s55
	s_mov_b32 s16, s56
	s_mov_b64 s[20:21], s[12:13]
	s_mov_b64 s[18:19], s[14:15]
	s_cbranch_vccnz .LBB0_2020
	s_waitcnt vmcnt(0)
	s_cmpk_gt_u32 s2, 0xff
	s_cbranch_scc1 .LBB0_2023
	s_barrier

.LBB0_2174:
	s_add_i32 s48, s88, s48
	s_and_b32 s49, s48, 7
	s_and_b32 s52, s31, 0xffffff00
	s_cmp_lt_i32 s48, 64
	s_cselect_b64 s[10:11], -1, 0
	s_and_b64 s[10:11], s[10:11], exec
	s_cselect_b32 s10, s52, s14
	s_ashr_i32 s11, s10, 31
	s_lshl_b64 s[12:13], s[10:11], 1
	s_lshl_b32 s10, s49, 20
	s_add_u32 s10, s3, s10
	s_addc_u32 s11, s4, 0
	s_add_u32 s10, s10, s12
	s_addc_u32 s11, s11, s13
	s_cmp_lt_i32 s48, 64
	s_cselect_b64 s[14:15], -1, 0
	ds_read_b128 v[18:21], v13
	ds_read_b128 v[22:25], v13 offset:1024
	ds_read_b128 v[26:29], v13 offset:2048
	ds_read_b128 v[30:33], v13 offset:3072
	s_and_b64 s[14:15], s[14:15], exec
	s_cselect_b32 s15, s11, s19
	s_cselect_b32 s14, s10, s18
	s_add_u32 s12, s22, s12
	s_addc_u32 s13, s23, s13
	s_cmp_lt_i32 s48, 64
	s_cselect_b64 s[20:21], -1, 0
	s_and_b64 vcc, s[20:21], exec
	s_cselect_b32 s21, s13, s17
	s_cselect_b32 s20, s12, s16
	s_add_u32 s54, s16, 0x80080
	s_addc_u32 s55, s17, 0
	s_mov_b32 m0, s36
	v_lshl_add_u64 v[68:69], s[54:55], 0, v[132:133]
	ds_read_b128 v[36:39], v14
	ds_read_b128 v[40:43], v14 offset:1024
	ds_read_b128 v[44:47], v14 offset:2048
	ds_read_b128 v[48:51], v14 offset:3072
	ds_read_b128 v[52:55], v14 offset:4096
	ds_read_b128 v[56:59], v14 offset:5120
	ds_read_b128 v[60:63], v14 offset:6144
	ds_read_b128 v[64:67], v14 offset:7168
	global_load_lds_dwordx4 v[68:69], off
	v_lshl_add_u64 v[68:69], s[54:55], 0, v[134:135]
	s_mov_b32 m0, s37
	s_nop 0
	global_load_lds_dwordx4 v[68:69], off
	s_waitcnt lgkmcnt(8)
	s_barrier
	s_waitcnt lgkmcnt(0)
	s_setprio 1
	s_waitcnt lgkmcnt(0)
	v_mfma_f32_16x16x32_bf16 v[68:71], v[36:39], v[18:21], 0
	v_mfma_f32_16x16x32_bf16 v[76:79], v[44:47], v[18:21], 0
	v_mfma_f32_16x16x32_bf16 v[84:87], v[52:55], v[18:21], 0
	v_mfma_f32_16x16x32_bf16 v[18:21], v[60:63], v[18:21], 0
	v_mfma_f32_16x16x32_bf16 v[68:71], v[40:43], v[22:25], v[68:71]
	v_mfma_f32_16x16x32_bf16 v[72:75], v[36:39], v[26:29], 0
	v_mfma_f32_16x16x32_bf16 v[76:79], v[48:51], v[22:25], v[76:79]
	v_mfma_f32_16x16x32_bf16 v[80:83], v[44:47], v[26:29], 0
	v_mfma_f32_16x16x32_bf16 v[84:87], v[56:59], v[22:25], v[84:87]
	v_mfma_f32_16x16x32_bf16 v[88:91], v[52:55], v[26:29], 0
	v_mfma_f32_16x16x32_bf16 v[18:21], v[64:67], v[22:25], v[18:21]
	v_mfma_f32_16x16x32_bf16 v[22:25], v[60:63], v[26:29], 0
	v_mfma_f32_16x16x32_bf16 v[72:75], v[40:43], v[30:33], v[72:75]
	v_mfma_f32_16x16x32_bf16 v[80:83], v[48:51], v[30:33], v[80:83]
	v_mfma_f32_16x16x32_bf16 v[88:91], v[56:59], v[30:33], v[88:91]
	v_mfma_f32_16x16x32_bf16 v[22:25], v[64:67], v[30:33], v[22:25]
	s_setprio 0
	s_barrier
	v_lshl_add_u64 v[136:137], s[18:19], 0, v[132:133]
	s_mov_b32 m0, s40
	v_lshl_add_u64 v[100:101], v[136:137], 0, s[6:7]
	v_lshl_add_u64 v[138:139], s[18:19], 0, v[134:135]
	ds_read_b128 v[26:29], v15
	ds_read_b128 v[30:33], v15 offset:1024
	ds_read_b128 v[92:95], v15 offset:2048
	ds_read_b128 v[96:99], v15 offset:3072
	global_load_lds_dwordx4 v[100:101], off
	v_lshl_add_u64 v[100:101], v[138:139], 0, s[6:7]
	s_mov_b32 m0, s41
	s_nop 0
	global_load_lds_dwordx4 v[100:101], off
	s_barrier
	s_waitcnt lgkmcnt(0)
	s_setprio 1
	s_waitcnt lgkmcnt(0)
	v_mfma_f32_16x16x32_bf16 v[100:103], v[36:39], v[26:29], 0
	v_mfma_f32_16x16x32_bf16 v[36:39], v[36:39], v[92:95], 0
	v_mfma_f32_16x16x32_bf16 v[100:103], v[40:43], v[30:33], v[100:103]
	v_mfma_f32_16x16x32_bf16 v[36:39], v[40:43], v[96:99], v[36:39]
	v_mfma_f32_16x16x32_bf16 v[40:43], v[44:47], v[26:29], 0
	v_mfma_f32_16x16x32_bf16 v[44:47], v[44:47], v[92:95], 0
	v_mfma_f32_16x16x32_bf16 v[40:43], v[48:51], v[30:33], v[40:43]
	v_mfma_f32_16x16x32_bf16 v[44:47], v[48:51], v[96:99], v[44:47]
	v_mfma_f32_16x16x32_bf16 v[48:51], v[52:55], v[26:29], 0
	v_mfma_f32_16x16x32_bf16 v[26:29], v[60:63], v[26:29], 0
	v_mfma_f32_16x16x32_bf16 v[48:51], v[56:59], v[30:33], v[48:51]
	v_mfma_f32_16x16x32_bf16 v[52:55], v[52:55], v[92:95], 0
	v_mfma_f32_16x16x32_bf16 v[26:29], v[64:67], v[30:33], v[26:29]
	v_mfma_f32_16x16x32_bf16 v[30:33], v[60:63], v[92:95], 0
	v_mfma_f32_16x16x32_bf16 v[52:55], v[56:59], v[96:99], v[52:55]
	v_mfma_f32_16x16x32_bf16 v[30:33], v[64:67], v[96:99], v[30:33]
	s_setprio 0
	v_lshl_add_u64 v[140:141], s[16:17], 0, v[132:133]
	s_mov_b32 m0, s5
	v_lshl_add_u64 v[56:57], v[140:141], 0, s[6:7]
	v_lshl_add_u64 v[142:143], s[16:17], 0, v[134:135]
	s_barrier
	global_load_lds_dwordx4 v[56:57], off
	v_lshl_add_u64 v[56:57], v[142:143], 0, s[6:7]
	s_mov_b32 m0, s24
	s_nop 0
	global_load_lds_dwordx4 v[56:57], off
	s_barrier
	s_waitcnt lgkmcnt(0)
	s_setprio 1
	s_setprio 0
	s_barrier
	s_add_u32 s54, s18, 0x80100
	s_addc_u32 s55, s19, 0
	s_mov_b32 m0, s42
	v_lshl_add_u64 v[56:57], s[54:55], 0, v[132:133]
	global_load_lds_dwordx4 v[56:57], off
	v_lshl_add_u64 v[56:57], s[54:55], 0, v[134:135]
	s_mov_b32 m0, s43
	s_nop 0
	global_load_lds_dwordx4 v[56:57], off
	s_waitcnt vmcnt(6)
	s_barrier
	s_setprio 1
	s_setprio 0
	s_barrier
	ds_read_b128 v[56:59], v16
	ds_read_b128 v[60:63], v16 offset:1024
	ds_read_b128 v[64:67], v16 offset:2048
	ds_read_b128 v[92:95], v16 offset:3072
	s_add_u32 s54, s16, 0x80100
	s_addc_u32 s55, s17, 0
	s_mov_b32 m0, s25
	v_lshl_add_u64 v[144:145], s[54:55], 0, v[132:133]
	ds_read_b128 v[96:99], v14 offset:32768
	ds_read_b128 v[104:107], v14 offset:33792
	ds_read_b128 v[108:111], v14 offset:34816
	ds_read_b128 v[112:115], v14 offset:35840
	ds_read_b128 v[116:119], v14 offset:36864
	ds_read_b128 v[120:123], v14 offset:37888
	ds_read_b128 v[124:127], v14 offset:38912
	ds_read_b128 v[128:131], v14 offset:39936
	global_load_lds_dwordx4 v[144:145], off
	v_lshl_add_u64 v[144:145], s[54:55], 0, v[134:135]
	s_mov_b32 m0, s26
	s_nop 0
	global_load_lds_dwordx4 v[144:145], off
	s_waitcnt lgkmcnt(8)
	s_barrier
	s_waitcnt lgkmcnt(0)
	s_setprio 1
	s_waitcnt lgkmcnt(0)
	v_mfma_f32_16x16x32_bf16 v[68:71], v[96:99], v[56:59], v[68:71]
	v_mfma_f32_16x16x32_bf16 v[72:75], v[96:99], v[64:67], v[72:75]
	v_mfma_f32_16x16x32_bf16 v[76:79], v[108:111], v[56:59], v[76:79]
	v_mfma_f32_16x16x32_bf16 v[80:83], v[108:111], v[64:67], v[80:83]
	v_mfma_f32_16x16x32_bf16 v[84:87], v[116:119], v[56:59], v[84:87]
	v_mfma_f32_16x16x32_bf16 v[88:91], v[116:119], v[64:67], v[88:91]
	v_mfma_f32_16x16x32_bf16 v[18:21], v[124:127], v[56:59], v[18:21]
	v_mfma_f32_16x16x32_bf16 v[22:25], v[124:127], v[64:67], v[22:25]
	v_mfma_f32_16x16x32_bf16 v[68:71], v[104:107], v[60:63], v[68:71]
	v_mfma_f32_16x16x32_bf16 v[72:75], v[104:107], v[92:95], v[72:75]
	v_mfma_f32_16x16x32_bf16 v[76:79], v[112:115], v[60:63], v[76:79]
	v_mfma_f32_16x16x32_bf16 v[80:83], v[112:115], v[92:95], v[80:83]
	v_mfma_f32_16x16x32_bf16 v[84:87], v[120:123], v[60:63], v[84:87]
	v_mfma_f32_16x16x32_bf16 v[88:91], v[120:123], v[92:95], v[88:91]
	v_mfma_f32_16x16x32_bf16 v[18:21], v[128:131], v[60:63], v[18:21]
	v_mfma_f32_16x16x32_bf16 v[22:25], v[128:131], v[92:95], v[22:25]
	s_setprio 0
	s_barrier
	s_mov_b32 m0, s44
	v_lshl_add_u64 v[136:137], v[136:137], 0, s[8:9]
	ds_read_b128 v[56:59], v17
	ds_read_b128 v[60:63], v17 offset:1024
	ds_read_b128 v[64:67], v17 offset:2048
	ds_read_b128 v[92:95], v17 offset:3072
	global_load_lds_dwordx4 v[136:137], off
	v_lshl_add_u64 v[136:137], v[138:139], 0, s[8:9]
	s_mov_b32 m0, s45
	s_nop 0
	global_load_lds_dwordx4 v[136:137], off
	s_barrier
	s_waitcnt lgkmcnt(0)
	s_setprio 1
	s_waitcnt lgkmcnt(0)
	v_mfma_f32_16x16x32_bf16 v[100:103], v[96:99], v[56:59], v[100:103]
	v_mfma_f32_16x16x32_bf16 v[36:39], v[96:99], v[64:67], v[36:39]
	v_mfma_f32_16x16x32_bf16 v[40:43], v[108:111], v[56:59], v[40:43]
	v_mfma_f32_16x16x32_bf16 v[44:47], v[108:111], v[64:67], v[44:47]
	v_mfma_f32_16x16x32_bf16 v[48:51], v[116:119], v[56:59], v[48:51]
	v_mfma_f32_16x16x32_bf16 v[52:55], v[116:119], v[64:67], v[52:55]
	v_mfma_f32_16x16x32_bf16 v[26:29], v[124:127], v[56:59], v[26:29]
	v_mfma_f32_16x16x32_bf16 v[30:33], v[124:127], v[64:67], v[30:33]
	v_mfma_f32_16x16x32_bf16 v[100:103], v[104:107], v[60:63], v[100:103]
	v_mfma_f32_16x16x32_bf16 v[36:39], v[104:107], v[92:95], v[36:39]
	v_mfma_f32_16x16x32_bf16 v[40:43], v[112:115], v[60:63], v[40:43]
	v_mfma_f32_16x16x32_bf16 v[44:47], v[112:115], v[92:95], v[44:47]
	v_mfma_f32_16x16x32_bf16 v[48:51], v[120:123], v[60:63], v[48:51]
	v_mfma_f32_16x16x32_bf16 v[52:55], v[120:123], v[92:95], v[52:55]
	v_mfma_f32_16x16x32_bf16 v[26:29], v[128:131], v[60:63], v[26:29]
	v_mfma_f32_16x16x32_bf16 v[30:33], v[128:131], v[92:95], v[30:33]
	s_setprio 0
	s_mov_b32 m0, s27
	v_lshl_add_u64 v[56:57], v[140:141], 0, s[8:9]
	s_barrier
	global_load_lds_dwordx4 v[56:57], off
	v_lshl_add_u64 v[56:57], v[142:143], 0, s[8:9]
	s_mov_b32 m0, s29
	s_nop 0
	global_load_lds_dwordx4 v[56:57], off
	s_barrier
	s_waitcnt lgkmcnt(0)
	s_setprio 1
	s_setprio 0
	s_barrier
	s_add_u32 s18, s18, 0x80180
	s_addc_u32 s19, s19, 0
	s_mov_b32 m0, s46
	v_lshl_add_u64 v[56:57], s[18:19], 0, v[132:133]
	global_load_lds_dwordx4 v[56:57], off
	v_lshl_add_u64 v[56:57], s[18:19], 0, v[134:135]
	s_mov_b32 m0, s47
	s_nop 0
	global_load_lds_dwordx4 v[56:57], off
	s_waitcnt vmcnt(6)
	s_barrier
	s_setprio 1
	s_setprio 0
	s_barrier
	ds_read_b128 v[56:59], v13
	ds_read_b128 v[60:63], v13 offset:1024
	ds_read_b128 v[64:67], v13 offset:2048
	ds_read_b128 v[92:95], v13 offset:3072
	s_add_u32 s16, s16, 0x80180
	s_addc_u32 s17, s17, 0
	s_mov_b32 m0, s36
	v_lshl_add_u64 v[136:137], s[16:17], 0, v[132:133]
	ds_read_b128 v[96:99], v14
	ds_read_b128 v[104:107], v14 offset:1024
	ds_read_b128 v[108:111], v14 offset:2048
	ds_read_b128 v[112:115], v14 offset:3072
	ds_read_b128 v[116:119], v14 offset:4096
	ds_read_b128 v[120:123], v14 offset:5120
	ds_read_b128 v[124:127], v14 offset:6144
	ds_read_b128 v[128:131], v14 offset:7168
	global_load_lds_dwordx4 v[136:137], off
	v_lshl_add_u64 v[136:137], s[16:17], 0, v[134:135]
	s_mov_b32 m0, s37
	s_nop 0
	global_load_lds_dwordx4 v[136:137], off
	s_waitcnt lgkmcnt(8)
	s_barrier
	s_waitcnt lgkmcnt(0)
	s_setprio 1
	s_waitcnt lgkmcnt(0)
	v_mfma_f32_16x16x32_bf16 v[68:71], v[96:99], v[56:59], v[68:71]
	v_mfma_f32_16x16x32_bf16 v[72:75], v[96:99], v[64:67], v[72:75]
	v_mfma_f32_16x16x32_bf16 v[76:79], v[108:111], v[56:59], v[76:79]
	v_mfma_f32_16x16x32_bf16 v[80:83], v[108:111], v[64:67], v[80:83]
	v_mfma_f32_16x16x32_bf16 v[84:87], v[116:119], v[56:59], v[84:87]
	v_mfma_f32_16x16x32_bf16 v[88:91], v[116:119], v[64:67], v[88:91]
	v_mfma_f32_16x16x32_bf16 v[18:21], v[124:127], v[56:59], v[18:21]
	v_mfma_f32_16x16x32_bf16 v[22:25], v[124:127], v[64:67], v[22:25]
	v_mfma_f32_16x16x32_bf16 v[68:71], v[104:107], v[60:63], v[68:71]
	v_mfma_f32_16x16x32_bf16 v[72:75], v[104:107], v[92:95], v[72:75]
	v_mfma_f32_16x16x32_bf16 v[76:79], v[112:115], v[60:63], v[76:79]
	v_mfma_f32_16x16x32_bf16 v[80:83], v[112:115], v[92:95], v[80:83]
	v_mfma_f32_16x16x32_bf16 v[84:87], v[120:123], v[60:63], v[84:87]
	v_mfma_f32_16x16x32_bf16 v[88:91], v[120:123], v[92:95], v[88:91]
	v_mfma_f32_16x16x32_bf16 v[18:21], v[128:131], v[60:63], v[18:21]
	v_mfma_f32_16x16x32_bf16 v[22:25], v[128:131], v[92:95], v[22:25]
	s_setprio 0
	s_barrier
	s_mov_b32 m0, s40
	v_lshl_add_u64 v[136:137], s[14:15], 0, v[132:133]
	ds_read_b128 v[56:59], v15
	ds_read_b128 v[60:63], v15 offset:1024
	ds_read_b128 v[64:67], v15 offset:2048
	ds_read_b128 v[92:95], v15 offset:3072
	global_load_lds_dwordx4 v[136:137], off
	v_lshl_add_u64 v[138:139], s[14:15], 0, v[134:135]
	s_mov_b32 m0, s41
	s_nop 0
	global_load_lds_dwordx4 v[138:139], off
	s_barrier
	s_waitcnt lgkmcnt(0)
	s_setprio 1
	s_waitcnt lgkmcnt(0)
	v_mfma_f32_16x16x32_bf16 v[100:103], v[96:99], v[56:59], v[100:103]
	v_mfma_f32_16x16x32_bf16 v[36:39], v[96:99], v[64:67], v[36:39]
	v_mfma_f32_16x16x32_bf16 v[40:43], v[108:111], v[56:59], v[40:43]
	v_mfma_f32_16x16x32_bf16 v[44:47], v[108:111], v[64:67], v[44:47]
	v_mfma_f32_16x16x32_bf16 v[48:51], v[116:119], v[56:59], v[48:51]
	v_mfma_f32_16x16x32_bf16 v[52:55], v[116:119], v[64:67], v[52:55]
	v_mfma_f32_16x16x32_bf16 v[26:29], v[124:127], v[56:59], v[26:29]
	v_mfma_f32_16x16x32_bf16 v[30:33], v[124:127], v[64:67], v[30:33]
	v_mfma_f32_16x16x32_bf16 v[100:103], v[104:107], v[60:63], v[100:103]
	v_mfma_f32_16x16x32_bf16 v[36:39], v[104:107], v[92:95], v[36:39]
	v_mfma_f32_16x16x32_bf16 v[40:43], v[112:115], v[60:63], v[40:43]
	v_mfma_f32_16x16x32_bf16 v[44:47], v[112:115], v[92:95], v[44:47]
	v_mfma_f32_16x16x32_bf16 v[48:51], v[120:123], v[60:63], v[48:51]
	v_mfma_f32_16x16x32_bf16 v[52:55], v[120:123], v[92:95], v[52:55]
	v_mfma_f32_16x16x32_bf16 v[26:29], v[128:131], v[60:63], v[26:29]
	v_mfma_f32_16x16x32_bf16 v[30:33], v[128:131], v[92:95], v[30:33]
	s_setprio 0
	s_mov_b32 m0, s5
	v_lshl_add_u64 v[140:141], s[20:21], 0, v[132:133]
	s_barrier
	global_load_lds_dwordx4 v[140:141], off
	v_lshl_add_u64 v[142:143], s[20:21], 0, v[134:135]
	s_mov_b32 m0, s24
	s_nop 0
	global_load_lds_dwordx4 v[142:143], off
	s_barrier
	s_waitcnt lgkmcnt(0)
	s_setprio 1
	s_setprio 0
	s_barrier
	s_add_u32 s16, s14, 0x80000
	s_addc_u32 s17, s15, 0
	s_mov_b32 m0, s42
	v_lshl_add_u64 v[56:57], s[16:17], 0, v[132:133]
	global_load_lds_dwordx4 v[56:57], off
	v_lshl_add_u64 v[56:57], s[16:17], 0, v[134:135]
	s_mov_b32 m0, s43
	s_nop 0
	global_load_lds_dwordx4 v[56:57], off
	s_waitcnt vmcnt(6)
	s_barrier
	s_setprio 1
	s_setprio 0
	s_barrier
	ds_read_b128 v[56:59], v16
	ds_read_b128 v[60:63], v16 offset:1024
	ds_read_b128 v[64:67], v16 offset:2048
	ds_read_b128 v[92:95], v16 offset:3072
	s_add_u32 s16, s20, 0x80000
	s_addc_u32 s17, s21, 0
	s_mov_b32 m0, s25
	v_lshl_add_u64 v[144:145], s[16:17], 0, v[132:133]
	ds_read_b128 v[96:99], v14 offset:32768
	ds_read_b128 v[104:107], v14 offset:33792
	ds_read_b128 v[108:111], v14 offset:34816
	ds_read_b128 v[112:115], v14 offset:35840
	ds_read_b128 v[116:119], v14 offset:36864
	ds_read_b128 v[120:123], v14 offset:37888
	ds_read_b128 v[124:127], v14 offset:38912
	ds_read_b128 v[128:131], v14 offset:39936
	global_load_lds_dwordx4 v[144:145], off
	v_lshl_add_u64 v[144:145], s[16:17], 0, v[134:135]
	s_mov_b32 m0, s26
	s_nop 0
	global_load_lds_dwordx4 v[144:145], off
	s_waitcnt lgkmcnt(8)
	s_barrier
	s_waitcnt lgkmcnt(0)
	s_setprio 1
	s_waitcnt lgkmcnt(0)
	v_mfma_f32_16x16x32_bf16 v[68:71], v[96:99], v[56:59], v[68:71]
	v_mfma_f32_16x16x32_bf16 v[72:75], v[96:99], v[64:67], v[72:75]
	v_mfma_f32_16x16x32_bf16 v[76:79], v[108:111], v[56:59], v[76:79]
	v_mfma_f32_16x16x32_bf16 v[80:83], v[108:111], v[64:67], v[80:83]
	v_mfma_f32_16x16x32_bf16 v[84:87], v[116:119], v[56:59], v[84:87]
	v_mfma_f32_16x16x32_bf16 v[88:91], v[116:119], v[64:67], v[88:91]
	v_mfma_f32_16x16x32_bf16 v[18:21], v[124:127], v[56:59], v[18:21]
	v_mfma_f32_16x16x32_bf16 v[22:25], v[124:127], v[64:67], v[22:25]
	v_mfma_f32_16x16x32_bf16 v[68:71], v[104:107], v[60:63], v[68:71]
	v_mfma_f32_16x16x32_bf16 v[72:75], v[104:107], v[92:95], v[72:75]
	v_mfma_f32_16x16x32_bf16 v[76:79], v[112:115], v[60:63], v[76:79]
	v_mfma_f32_16x16x32_bf16 v[80:83], v[112:115], v[92:95], v[80:83]
	v_mfma_f32_16x16x32_bf16 v[84:87], v[120:123], v[60:63], v[84:87]
	v_mfma_f32_16x16x32_bf16 v[88:91], v[120:123], v[92:95], v[88:91]
	v_mfma_f32_16x16x32_bf16 v[18:21], v[128:131], v[60:63], v[18:21]
	v_mfma_f32_16x16x32_bf16 v[22:25], v[128:131], v[92:95], v[22:25]
	s_setprio 0
	s_barrier
	s_mov_b32 m0, s44
	v_lshl_add_u64 v[136:137], v[136:137], 0, s[0:1]
	ds_read_b128 v[56:59], v17
	ds_read_b128 v[60:63], v17 offset:1024
	ds_read_b128 v[64:67], v17 offset:2048
	ds_read_b128 v[92:95], v17 offset:3072
	global_load_lds_dwordx4 v[136:137], off
	v_lshl_add_u64 v[136:137], v[138:139], 0, s[0:1]
	s_mov_b32 m0, s45
	s_nop 0
	global_load_lds_dwordx4 v[136:137], off
	s_barrier
	s_waitcnt lgkmcnt(0)
	s_setprio 1
	s_waitcnt lgkmcnt(0)
	v_mfma_f32_16x16x32_bf16 v[100:103], v[96:99], v[56:59], v[100:103]
	v_mfma_f32_16x16x32_bf16 v[36:39], v[96:99], v[64:67], v[36:39]
	v_mfma_f32_16x16x32_bf16 v[40:43], v[108:111], v[56:59], v[40:43]
	v_mfma_f32_16x16x32_bf16 v[44:47], v[108:111], v[64:67], v[44:47]
	v_mfma_f32_16x16x32_bf16 v[48:51], v[116:119], v[56:59], v[48:51]
	v_mfma_f32_16x16x32_bf16 v[52:55], v[116:119], v[64:67], v[52:55]
	v_mfma_f32_16x16x32_bf16 v[26:29], v[124:127], v[56:59], v[26:29]
	v_mfma_f32_16x16x32_bf16 v[30:33], v[124:127], v[64:67], v[30:33]
	v_mfma_f32_16x16x32_bf16 v[100:103], v[104:107], v[60:63], v[100:103]
	v_mfma_f32_16x16x32_bf16 v[36:39], v[104:107], v[92:95], v[36:39]
	v_mfma_f32_16x16x32_bf16 v[40:43], v[112:115], v[60:63], v[40:43]
	v_mfma_f32_16x16x32_bf16 v[44:47], v[112:115], v[92:95], v[44:47]
	v_mfma_f32_16x16x32_bf16 v[48:51], v[120:123], v[60:63], v[48:51]
	v_mfma_f32_16x16x32_bf16 v[52:55], v[120:123], v[92:95], v[52:55]
	v_mfma_f32_16x16x32_bf16 v[26:29], v[128:131], v[60:63], v[26:29]
	v_mfma_f32_16x16x32_bf16 v[30:33], v[128:131], v[92:95], v[30:33]
	s_setprio 0
	s_mov_b32 m0, s27
	v_lshl_add_u64 v[56:57], v[140:141], 0, s[0:1]
	s_barrier
	global_load_lds_dwordx4 v[56:57], off
	v_lshl_add_u64 v[56:57], v[142:143], 0, s[0:1]
	s_mov_b32 m0, s29
	s_nop 0
	global_load_lds_dwordx4 v[56:57], off
	s_barrier
	s_waitcnt lgkmcnt(0)
	s_setprio 1
	s_setprio 0
	s_barrier
	s_add_u32 s14, s14, 0x80080
	s_addc_u32 s15, s15, 0
	s_mov_b32 m0, s46
	v_lshl_add_u64 v[56:57], s[14:15], 0, v[132:133]
	global_load_lds_dwordx4 v[56:57], off
	v_lshl_add_u64 v[56:57], s[14:15], 0, v[134:135]
	s_mov_b32 m0, s47
	s_nop 0
	global_load_lds_dwordx4 v[56:57], off
	s_waitcnt vmcnt(6)
	s_barrier
	s_setprio 1
	s_setprio 0
	v_lshl_or_b32 v2, s30, 8, v12
	v_lshlrev_b64 v[56:57], 2, v[2:3]
	v_lshl_add_u64 v[58:59], v[4:5], 0, v[56:57]
	s_barrier
	s_mov_b64 s[98:99], 0x2000
	s_mov_b64 s[100:101], 0x1a000
	v_mbcnt_lo_u32_b32 v60, -1, 0
	v_mbcnt_hi_u32_b32 v60, -1, v60
	v_and_b32_e32 v61, 15, v60
	v_lshrrev_b32_e32 v60, 4, v60
	v_lshlrev_b32_e32 v60, 2, v60
	v_sub_u32_e32 v60, v60, v61
	v_mul_i32_i24_e32 v60, 0x1ffc, v60
	v_ashrrev_i32_e32 v61, 31, v60
	v_lshl_add_u64 v[58:59], v[60:61], 0, v[58:59]
	global_atomic_add_f32 v[58:59], v68, off
	global_atomic_add_f32 v[58:59], v72, off offset:64
	global_atomic_add_f32 v[58:59], v100, off offset:512
	global_atomic_add_f32 v[58:59], v36, off offset:576
	v_lshl_add_u64 v[60:61], v[58:59], 0, s[98:99]
	global_atomic_add_f32 v[60:61], v69, off
	global_atomic_add_f32 v[60:61], v73, off offset:64
	global_atomic_add_f32 v[60:61], v101, off offset:512
	global_atomic_add_f32 v[60:61], v37, off offset:576
	v_lshl_add_u64 v[58:59], v[60:61], 0, s[98:99]
	global_atomic_add_f32 v[58:59], v70, off
	global_atomic_add_f32 v[58:59], v74, off offset:64
	global_atomic_add_f32 v[58:59], v102, off offset:512
	global_atomic_add_f32 v[58:59], v38, off offset:576
	v_lshl_add_u64 v[60:61], v[58:59], 0, s[98:99]
	global_atomic_add_f32 v[60:61], v71, off
	global_atomic_add_f32 v[60:61], v75, off offset:64
	global_atomic_add_f32 v[60:61], v103, off offset:512
	global_atomic_add_f32 v[60:61], v39, off offset:576
	v_lshl_add_u64 v[58:59], v[60:61], 0, s[100:101]
	global_atomic_add_f32 v[58:59], v76, off
	global_atomic_add_f32 v[58:59], v80, off offset:64
	global_atomic_add_f32 v[58:59], v40, off offset:512
	global_atomic_add_f32 v[58:59], v44, off offset:576
	v_lshl_add_u64 v[60:61], v[58:59], 0, s[98:99]
	global_atomic_add_f32 v[60:61], v77, off
	global_atomic_add_f32 v[60:61], v81, off offset:64
	global_atomic_add_f32 v[60:61], v41, off offset:512
	global_atomic_add_f32 v[60:61], v45, off offset:576
	v_lshl_add_u64 v[58:59], v[60:61], 0, s[98:99]
	global_atomic_add_f32 v[58:59], v78, off
	global_atomic_add_f32 v[58:59], v82, off offset:64
	global_atomic_add_f32 v[58:59], v42, off offset:512
	global_atomic_add_f32 v[58:59], v46, off offset:576
	v_lshl_add_u64 v[60:61], v[58:59], 0, s[98:99]
	global_atomic_add_f32 v[60:61], v79, off
	global_atomic_add_f32 v[60:61], v83, off offset:64
	global_atomic_add_f32 v[60:61], v43, off offset:512
	global_atomic_add_f32 v[60:61], v47, off offset:576
	v_lshl_add_u64 v[58:59], v[60:61], 0, s[100:101]
	global_atomic_add_f32 v[58:59], v84, off
	global_atomic_add_f32 v[58:59], v88, off offset:64
	global_atomic_add_f32 v[58:59], v48, off offset:512
	global_atomic_add_f32 v[58:59], v52, off offset:576
	v_lshl_add_u64 v[60:61], v[58:59], 0, s[98:99]
	global_atomic_add_f32 v[60:61], v85, off
	global_atomic_add_f32 v[60:61], v89, off offset:64
	global_atomic_add_f32 v[60:61], v49, off offset:512
	global_atomic_add_f32 v[60:61], v53, off offset:576
	v_lshl_add_u64 v[58:59], v[60:61], 0, s[98:99]
	global_atomic_add_f32 v[58:59], v86, off
	global_atomic_add_f32 v[58:59], v90, off offset:64
	global_atomic_add_f32 v[58:59], v50, off offset:512
	global_atomic_add_f32 v[58:59], v54, off offset:576
	v_lshl_add_u64 v[60:61], v[58:59], 0, s[98:99]
	global_atomic_add_f32 v[60:61], v87, off
	global_atomic_add_f32 v[60:61], v91, off offset:64
	global_atomic_add_f32 v[60:61], v51, off offset:512
	global_atomic_add_f32 v[60:61], v55, off offset:576
	v_lshl_add_u64 v[58:59], v[60:61], 0, s[100:101]
	global_atomic_add_f32 v[58:59], v18, off
	global_atomic_add_f32 v[58:59], v22, off offset:64
	global_atomic_add_f32 v[58:59], v26, off offset:512
	global_atomic_add_f32 v[58:59], v30, off offset:576
	v_lshl_add_u64 v[60:61], v[58:59], 0, s[98:99]
	global_atomic_add_f32 v[60:61], v19, off
	global_atomic_add_f32 v[60:61], v23, off offset:64
	global_atomic_add_f32 v[60:61], v27, off offset:512
	global_atomic_add_f32 v[60:61], v31, off offset:576
	v_lshl_add_u64 v[58:59], v[60:61], 0, s[98:99]
	global_atomic_add_f32 v[58:59], v20, off
	global_atomic_add_f32 v[58:59], v24, off offset:64
	global_atomic_add_f32 v[58:59], v28, off offset:512
	global_atomic_add_f32 v[58:59], v32, off offset:576
	v_lshl_add_u64 v[60:61], v[58:59], 0, s[98:99]
	global_atomic_add_f32 v[60:61], v21, off
	global_atomic_add_f32 v[60:61], v25, off offset:64
	global_atomic_add_f32 v[60:61], v29, off offset:512
	global_atomic_add_f32 v[60:61], v33, off offset:576
	s_add_i32 s31, s31, s33
	s_mov_b32 s30, s49
	s_mov_b32 s14, s52
	s_mov_b64 s[18:19], s[10:11]
	s_mov_b64 s[16:17], s[12:13]
	s_cbranch_vccnz .LBB0_2174
	s_waitcnt vmcnt(0)
	s_cmpk_gt_u32 s2, 0xff
	s_cbranch_scc1 .LBB0_2177
	s_barrier

.LBB0_2611:
	ds_read_b128 v[18:21], v12
	ds_read_b128 v[22:25], v12 offset:1024
	ds_read_b128 v[26:29], v12 offset:2048
	ds_read_b128 v[30:33], v12 offset:3072
	s_add_u32 s14, s22, s14
	s_addc_u32 s15, s23, s15
	s_and_b64 s[20:21], s[20:21], exec
	s_cselect_b32 s21, s15, s17
	s_cselect_b32 s20, s14, s16
	s_add_u32 s50, s16, 0x160080
	s_addc_u32 s51, s17, 0
	s_mov_b32 m0, s36
	v_lshl_add_u64 v[68:69], s[50:51], 0, v[132:133]
	ds_read_b128 v[36:39], v13
	ds_read_b128 v[40:43], v13 offset:1024
	ds_read_b128 v[44:47], v13 offset:2048
	ds_read_b128 v[48:51], v13 offset:3072
	ds_read_b128 v[52:55], v13 offset:4096
	ds_read_b128 v[56:59], v13 offset:5120
	ds_read_b128 v[60:63], v13 offset:6144
	ds_read_b128 v[64:67], v13 offset:7168
	global_load_lds_dwordx4 v[68:69], off
	v_lshl_add_u64 v[68:69], s[50:51], 0, v[134:135]
	s_mov_b32 m0, s37
	s_nop 0
	global_load_lds_dwordx4 v[68:69], off
	s_waitcnt lgkmcnt(8)
	s_barrier
	s_waitcnt lgkmcnt(0)
	s_setprio 1
	s_waitcnt lgkmcnt(0)
	v_mfma_f32_16x16x32_bf16 v[68:71], v[36:39], v[18:21], 0
	v_mfma_f32_16x16x32_bf16 v[76:79], v[44:47], v[18:21], 0
	v_mfma_f32_16x16x32_bf16 v[84:87], v[52:55], v[18:21], 0
	v_mfma_f32_16x16x32_bf16 v[18:21], v[60:63], v[18:21], 0
	v_mfma_f32_16x16x32_bf16 v[68:71], v[40:43], v[22:25], v[68:71]
	v_mfma_f32_16x16x32_bf16 v[72:75], v[36:39], v[26:29], 0
	v_mfma_f32_16x16x32_bf16 v[76:79], v[48:51], v[22:25], v[76:79]
	v_mfma_f32_16x16x32_bf16 v[80:83], v[44:47], v[26:29], 0
	v_mfma_f32_16x16x32_bf16 v[84:87], v[56:59], v[22:25], v[84:87]
	v_mfma_f32_16x16x32_bf16 v[88:91], v[52:55], v[26:29], 0
	v_mfma_f32_16x16x32_bf16 v[18:21], v[64:67], v[22:25], v[18:21]
	v_mfma_f32_16x16x32_bf16 v[22:25], v[60:63], v[26:29], 0
	v_mfma_f32_16x16x32_bf16 v[72:75], v[40:43], v[30:33], v[72:75]
	v_mfma_f32_16x16x32_bf16 v[80:83], v[48:51], v[30:33], v[80:83]
	v_mfma_f32_16x16x32_bf16 v[88:91], v[56:59], v[30:33], v[88:91]
	v_mfma_f32_16x16x32_bf16 v[22:25], v[64:67], v[30:33], v[22:25]
	s_setprio 0
	s_barrier
	v_lshl_add_u64 v[136:137], s[18:19], 0, v[132:133]
	s_mov_b32 m0, s38
	v_lshl_add_u64 v[100:101], v[136:137], 0, s[6:7]
	v_lshl_add_u64 v[138:139], s[18:19], 0, v[134:135]
	ds_read_b128 v[26:29], v14
	ds_read_b128 v[30:33], v14 offset:1024
	ds_read_b128 v[92:95], v14 offset:2048
	ds_read_b128 v[96:99], v14 offset:3072
	global_load_lds_dwordx4 v[100:101], off
	v_lshl_add_u64 v[100:101], v[138:139], 0, s[6:7]
	s_mov_b32 m0, s39
	s_nop 0
	global_load_lds_dwordx4 v[100:101], off
	s_barrier
	s_waitcnt lgkmcnt(0)
	s_setprio 1
	s_waitcnt lgkmcnt(0)
	v_mfma_f32_16x16x32_bf16 v[100:103], v[36:39], v[26:29], 0
	v_mfma_f32_16x16x32_bf16 v[36:39], v[36:39], v[92:95], 0
	v_mfma_f32_16x16x32_bf16 v[100:103], v[40:43], v[30:33], v[100:103]
	v_mfma_f32_16x16x32_bf16 v[36:39], v[40:43], v[96:99], v[36:39]
	v_mfma_f32_16x16x32_bf16 v[40:43], v[44:47], v[26:29], 0
	v_mfma_f32_16x16x32_bf16 v[44:47], v[44:47], v[92:95], 0
	v_mfma_f32_16x16x32_bf16 v[40:43], v[48:51], v[30:33], v[40:43]
	v_mfma_f32_16x16x32_bf16 v[44:47], v[48:51], v[96:99], v[44:47]
	v_mfma_f32_16x16x32_bf16 v[48:51], v[52:55], v[26:29], 0
	v_mfma_f32_16x16x32_bf16 v[26:29], v[60:63], v[26:29], 0
	v_mfma_f32_16x16x32_bf16 v[48:51], v[56:59], v[30:33], v[48:51]
	v_mfma_f32_16x16x32_bf16 v[52:55], v[52:55], v[92:95], 0
	v_mfma_f32_16x16x32_bf16 v[26:29], v[64:67], v[30:33], v[26:29]
	v_mfma_f32_16x16x32_bf16 v[30:33], v[60:63], v[92:95], 0
	v_mfma_f32_16x16x32_bf16 v[52:55], v[56:59], v[96:99], v[52:55]
	v_mfma_f32_16x16x32_bf16 v[30:33], v[64:67], v[96:99], v[30:33]
	s_setprio 0
	v_lshl_add_u64 v[140:141], s[16:17], 0, v[132:133]
	s_mov_b32 m0, s5
	v_lshl_add_u64 v[56:57], v[140:141], 0, s[6:7]
	v_lshl_add_u64 v[142:143], s[16:17], 0, v[134:135]
	s_barrier
	global_load_lds_dwordx4 v[56:57], off
	v_lshl_add_u64 v[56:57], v[142:143], 0, s[6:7]
	s_mov_b32 m0, s24
	s_nop 0
	global_load_lds_dwordx4 v[56:57], off
	s_barrier
	s_waitcnt lgkmcnt(0)
	s_setprio 1
	s_setprio 0
	s_barrier
	s_add_u32 s50, s18, 0x160100
	s_addc_u32 s51, s19, 0
	s_mov_b32 m0, s40
	v_lshl_add_u64 v[56:57], s[50:51], 0, v[132:133]
	global_load_lds_dwordx4 v[56:57], off
	v_lshl_add_u64 v[56:57], s[50:51], 0, v[134:135]
	s_mov_b32 m0, s41
	s_nop 0
	global_load_lds_dwordx4 v[56:57], off
	s_waitcnt vmcnt(6)
	s_barrier
	s_setprio 1
	s_setprio 0
	s_barrier
	ds_read_b128 v[56:59], v15
	ds_read_b128 v[60:63], v15 offset:1024
	ds_read_b128 v[64:67], v15 offset:2048
	ds_read_b128 v[92:95], v15 offset:3072
	s_add_u32 s50, s16, 0x160100
	s_addc_u32 s51, s17, 0
	s_mov_b32 m0, s25
	v_lshl_add_u64 v[144:145], s[50:51], 0, v[132:133]
	ds_read_b128 v[96:99], v13 offset:32768
	ds_read_b128 v[104:107], v13 offset:33792
	ds_read_b128 v[108:111], v13 offset:34816
	ds_read_b128 v[112:115], v13 offset:35840
	ds_read_b128 v[116:119], v13 offset:36864
	ds_read_b128 v[120:123], v13 offset:37888
	ds_read_b128 v[124:127], v13 offset:38912
	ds_read_b128 v[128:131], v13 offset:39936
	global_load_lds_dwordx4 v[144:145], off
	v_lshl_add_u64 v[144:145], s[50:51], 0, v[134:135]
	s_mov_b32 m0, s26
	s_nop 0
	global_load_lds_dwordx4 v[144:145], off
	s_waitcnt lgkmcnt(8)
	s_barrier
	s_waitcnt lgkmcnt(0)
	s_setprio 1
	s_waitcnt lgkmcnt(0)
	v_mfma_f32_16x16x32_bf16 v[68:71], v[96:99], v[56:59], v[68:71]
	v_mfma_f32_16x16x32_bf16 v[72:75], v[96:99], v[64:67], v[72:75]
	v_mfma_f32_16x16x32_bf16 v[76:79], v[108:111], v[56:59], v[76:79]
	v_mfma_f32_16x16x32_bf16 v[80:83], v[108:111], v[64:67], v[80:83]
	v_mfma_f32_16x16x32_bf16 v[84:87], v[116:119], v[56:59], v[84:87]
	v_mfma_f32_16x16x32_bf16 v[88:91], v[116:119], v[64:67], v[88:91]
	v_mfma_f32_16x16x32_bf16 v[18:21], v[124:127], v[56:59], v[18:21]
	v_mfma_f32_16x16x32_bf16 v[22:25], v[124:127], v[64:67], v[22:25]
	v_mfma_f32_16x16x32_bf16 v[68:71], v[104:107], v[60:63], v[68:71]
	v_mfma_f32_16x16x32_bf16 v[72:75], v[104:107], v[92:95], v[72:75]
	v_mfma_f32_16x16x32_bf16 v[76:79], v[112:115], v[60:63], v[76:79]
	v_mfma_f32_16x16x32_bf16 v[80:83], v[112:115], v[92:95], v[80:83]
	v_mfma_f32_16x16x32_bf16 v[84:87], v[120:123], v[60:63], v[84:87]
	v_mfma_f32_16x16x32_bf16 v[88:91], v[120:123], v[92:95], v[88:91]
	v_mfma_f32_16x16x32_bf16 v[18:21], v[128:131], v[60:63], v[18:21]
	v_mfma_f32_16x16x32_bf16 v[22:25], v[128:131], v[92:95], v[22:25]
	s_setprio 0
	s_barrier
	s_mov_b32 m0, s42
	v_lshl_add_u64 v[136:137], v[136:137], 0, s[8:9]
	ds_read_b128 v[56:59], v16
	ds_read_b128 v[60:63], v16 offset:1024
	ds_read_b128 v[64:67], v16 offset:2048
	ds_read_b128 v[92:95], v16 offset:3072
	global_load_lds_dwordx4 v[136:137], off
	v_lshl_add_u64 v[136:137], v[138:139], 0, s[8:9]
	s_mov_b32 m0, s43
	s_nop 0
	global_load_lds_dwordx4 v[136:137], off
	s_barrier
	s_waitcnt lgkmcnt(0)
	s_setprio 1
	s_waitcnt lgkmcnt(0)
	v_mfma_f32_16x16x32_bf16 v[100:103], v[96:99], v[56:59], v[100:103]
	v_mfma_f32_16x16x32_bf16 v[36:39], v[96:99], v[64:67], v[36:39]
	v_mfma_f32_16x16x32_bf16 v[40:43], v[108:111], v[56:59], v[40:43]
	v_mfma_f32_16x16x32_bf16 v[44:47], v[108:111], v[64:67], v[44:47]
	v_mfma_f32_16x16x32_bf16 v[48:51], v[116:119], v[56:59], v[48:51]
	v_mfma_f32_16x16x32_bf16 v[52:55], v[116:119], v[64:67], v[52:55]
	v_mfma_f32_16x16x32_bf16 v[26:29], v[124:127], v[56:59], v[26:29]
	v_mfma_f32_16x16x32_bf16 v[30:33], v[124:127], v[64:67], v[30:33]
	v_mfma_f32_16x16x32_bf16 v[100:103], v[104:107], v[60:63], v[100:103]
	v_mfma_f32_16x16x32_bf16 v[36:39], v[104:107], v[92:95], v[36:39]
	v_mfma_f32_16x16x32_bf16 v[40:43], v[112:115], v[60:63], v[40:43]
	v_mfma_f32_16x16x32_bf16 v[44:47], v[112:115], v[92:95], v[44:47]
	v_mfma_f32_16x16x32_bf16 v[48:51], v[120:123], v[60:63], v[48:51]
	v_mfma_f32_16x16x32_bf16 v[52:55], v[120:123], v[92:95], v[52:55]
	v_mfma_f32_16x16x32_bf16 v[26:29], v[128:131], v[60:63], v[26:29]
	v_mfma_f32_16x16x32_bf16 v[30:33], v[128:131], v[92:95], v[30:33]
	s_setprio 0
	s_mov_b32 m0, s29
	v_lshl_add_u64 v[56:57], v[140:141], 0, s[8:9]
	s_barrier
	global_load_lds_dwordx4 v[56:57], off
	v_lshl_add_u64 v[56:57], v[142:143], 0, s[8:9]
	s_mov_b32 m0, s30
	s_nop 0
	global_load_lds_dwordx4 v[56:57], off
	s_barrier
	s_waitcnt lgkmcnt(0)
	s_setprio 1
	s_setprio 0
	s_barrier
	s_add_u32 s18, s18, 0x160180
	s_addc_u32 s19, s19, 0
	s_mov_b32 m0, s44
	v_lshl_add_u64 v[56:57], s[18:19], 0, v[132:133]
	global_load_lds_dwordx4 v[56:57], off
	v_lshl_add_u64 v[56:57], s[18:19], 0, v[134:135]
	s_mov_b32 m0, s45
	s_nop 0
	global_load_lds_dwordx4 v[56:57], off
	s_waitcnt vmcnt(6)
	s_barrier
	s_setprio 1
	s_setprio 0
	s_barrier
	ds_read_b128 v[56:59], v12
	ds_read_b128 v[60:63], v12 offset:1024
	ds_read_b128 v[64:67], v12 offset:2048
	ds_read_b128 v[92:95], v12 offset:3072
	s_add_u32 s16, s16, 0x160180
	s_addc_u32 s17, s17, 0
	s_mov_b32 m0, s36
	v_lshl_add_u64 v[136:137], s[16:17], 0, v[132:133]
	ds_read_b128 v[96:99], v13
	ds_read_b128 v[104:107], v13 offset:1024
	ds_read_b128 v[108:111], v13 offset:2048
	ds_read_b128 v[112:115], v13 offset:3072
	ds_read_b128 v[116:119], v13 offset:4096
	ds_read_b128 v[120:123], v13 offset:5120
	ds_read_b128 v[124:127], v13 offset:6144
	ds_read_b128 v[128:131], v13 offset:7168
	global_load_lds_dwordx4 v[136:137], off
	v_lshl_add_u64 v[136:137], s[16:17], 0, v[134:135]
	s_mov_b32 m0, s37
	s_nop 0
	global_load_lds_dwordx4 v[136:137], off
	s_waitcnt lgkmcnt(8)
	s_barrier
	s_waitcnt lgkmcnt(0)
	s_setprio 1
	s_waitcnt lgkmcnt(0)
	v_mfma_f32_16x16x32_bf16 v[68:71], v[96:99], v[56:59], v[68:71]
	v_mfma_f32_16x16x32_bf16 v[72:75], v[96:99], v[64:67], v[72:75]
	v_mfma_f32_16x16x32_bf16 v[76:79], v[108:111], v[56:59], v[76:79]
	v_mfma_f32_16x16x32_bf16 v[80:83], v[108:111], v[64:67], v[80:83]
	v_mfma_f32_16x16x32_bf16 v[84:87], v[116:119], v[56:59], v[84:87]
	v_mfma_f32_16x16x32_bf16 v[88:91], v[116:119], v[64:67], v[88:91]
	v_mfma_f32_16x16x32_bf16 v[18:21], v[124:127], v[56:59], v[18:21]
	v_mfma_f32_16x16x32_bf16 v[22:25], v[124:127], v[64:67], v[22:25]
	v_mfma_f32_16x16x32_bf16 v[68:71], v[104:107], v[60:63], v[68:71]
	v_mfma_f32_16x16x32_bf16 v[72:75], v[104:107], v[92:95], v[72:75]
	v_mfma_f32_16x16x32_bf16 v[76:79], v[112:115], v[60:63], v[76:79]
	v_mfma_f32_16x16x32_bf16 v[80:83], v[112:115], v[92:95], v[80:83]
	v_mfma_f32_16x16x32_bf16 v[84:87], v[120:123], v[60:63], v[84:87]
	v_mfma_f32_16x16x32_bf16 v[88:91], v[120:123], v[92:95], v[88:91]
	v_mfma_f32_16x16x32_bf16 v[18:21], v[128:131], v[60:63], v[18:21]
	v_mfma_f32_16x16x32_bf16 v[22:25], v[128:131], v[92:95], v[22:25]
	s_setprio 0
	s_barrier
	s_mov_b32 m0, s38
	v_lshl_add_u64 v[136:137], s[10:11], 0, v[132:133]
	ds_read_b128 v[56:59], v14
	ds_read_b128 v[60:63], v14 offset:1024
	ds_read_b128 v[64:67], v14 offset:2048
	ds_read_b128 v[92:95], v14 offset:3072
	global_load_lds_dwordx4 v[136:137], off
	v_lshl_add_u64 v[138:139], s[10:11], 0, v[134:135]
	s_mov_b32 m0, s39
	s_nop 0
	global_load_lds_dwordx4 v[138:139], off
	s_barrier
	s_waitcnt lgkmcnt(0)
	s_setprio 1
	s_waitcnt lgkmcnt(0)
	v_mfma_f32_16x16x32_bf16 v[100:103], v[96:99], v[56:59], v[100:103]
	v_mfma_f32_16x16x32_bf16 v[36:39], v[96:99], v[64:67], v[36:39]
	v_mfma_f32_16x16x32_bf16 v[40:43], v[108:111], v[56:59], v[40:43]
	v_mfma_f32_16x16x32_bf16 v[44:47], v[108:111], v[64:67], v[44:47]
	v_mfma_f32_16x16x32_bf16 v[48:51], v[116:119], v[56:59], v[48:51]
	v_mfma_f32_16x16x32_bf16 v[52:55], v[116:119], v[64:67], v[52:55]
	v_mfma_f32_16x16x32_bf16 v[26:29], v[124:127], v[56:59], v[26:29]
	v_mfma_f32_16x16x32_bf16 v[30:33], v[124:127], v[64:67], v[30:33]
	v_mfma_f32_16x16x32_bf16 v[100:103], v[104:107], v[60:63], v[100:103]
	v_mfma_f32_16x16x32_bf16 v[36:39], v[104:107], v[92:95], v[36:39]
	v_mfma_f32_16x16x32_bf16 v[40:43], v[112:115], v[60:63], v[40:43]
	v_mfma_f32_16x16x32_bf16 v[44:47], v[112:115], v[92:95], v[44:47]
	v_mfma_f32_16x16x32_bf16 v[48:51], v[120:123], v[60:63], v[48:51]
	v_mfma_f32_16x16x32_bf16 v[52:55], v[120:123], v[92:95], v[52:55]
	v_mfma_f32_16x16x32_bf16 v[26:29], v[128:131], v[60:63], v[26:29]
	v_mfma_f32_16x16x32_bf16 v[30:33], v[128:131], v[92:95], v[30:33]
	s_setprio 0
	s_mov_b32 m0, s5
	v_lshl_add_u64 v[140:141], s[20:21], 0, v[132:133]
	s_barrier
	global_load_lds_dwordx4 v[140:141], off
	v_lshl_add_u64 v[142:143], s[20:21], 0, v[134:135]
	s_mov_b32 m0, s24
	s_nop 0
	global_load_lds_dwordx4 v[142:143], off
	s_barrier
	s_waitcnt lgkmcnt(0)
	s_setprio 1
	s_setprio 0
	s_barrier
	s_add_u32 s16, s10, 0x160000
	s_addc_u32 s17, s11, 0
	s_mov_b32 m0, s40
	v_lshl_add_u64 v[56:57], s[16:17], 0, v[132:133]
	global_load_lds_dwordx4 v[56:57], off
	v_lshl_add_u64 v[56:57], s[16:17], 0, v[134:135]
	s_mov_b32 m0, s41
	s_nop 0
	global_load_lds_dwordx4 v[56:57], off
	s_waitcnt vmcnt(6)
	s_barrier
	s_setprio 1
	s_setprio 0
	s_barrier
	ds_read_b128 v[56:59], v15
	ds_read_b128 v[60:63], v15 offset:1024
	ds_read_b128 v[64:67], v15 offset:2048
	ds_read_b128 v[92:95], v15 offset:3072
	s_add_u32 s16, s20, 0x160000
	s_addc_u32 s17, s21, 0
	s_mov_b32 m0, s25
	v_lshl_add_u64 v[144:145], s[16:17], 0, v[132:133]
	ds_read_b128 v[96:99], v13 offset:32768
	ds_read_b128 v[104:107], v13 offset:33792
	ds_read_b128 v[108:111], v13 offset:34816
	ds_read_b128 v[112:115], v13 offset:35840
	ds_read_b128 v[116:119], v13 offset:36864
	ds_read_b128 v[120:123], v13 offset:37888
	ds_read_b128 v[124:127], v13 offset:38912
	ds_read_b128 v[128:131], v13 offset:39936
	global_load_lds_dwordx4 v[144:145], off
	v_lshl_add_u64 v[144:145], s[16:17], 0, v[134:135]
	s_mov_b32 m0, s26
	s_nop 0
	global_load_lds_dwordx4 v[144:145], off
	s_waitcnt lgkmcnt(8)
	s_barrier
	s_waitcnt lgkmcnt(0)
	s_setprio 1
	s_waitcnt lgkmcnt(0)
	v_mfma_f32_16x16x32_bf16 v[68:71], v[96:99], v[56:59], v[68:71]
	v_mfma_f32_16x16x32_bf16 v[72:75], v[96:99], v[64:67], v[72:75]
	v_mfma_f32_16x16x32_bf16 v[76:79], v[108:111], v[56:59], v[76:79]
	v_mfma_f32_16x16x32_bf16 v[80:83], v[108:111], v[64:67], v[80:83]
	v_mfma_f32_16x16x32_bf16 v[84:87], v[116:119], v[56:59], v[84:87]
	v_mfma_f32_16x16x32_bf16 v[88:91], v[116:119], v[64:67], v[88:91]
	v_mfma_f32_16x16x32_bf16 v[18:21], v[124:127], v[56:59], v[18:21]
	v_mfma_f32_16x16x32_bf16 v[22:25], v[124:127], v[64:67], v[22:25]
	v_mfma_f32_16x16x32_bf16 v[68:71], v[104:107], v[60:63], v[68:71]
	v_mfma_f32_16x16x32_bf16 v[72:75], v[104:107], v[92:95], v[72:75]
	v_mfma_f32_16x16x32_bf16 v[76:79], v[112:115], v[60:63], v[76:79]
	v_mfma_f32_16x16x32_bf16 v[80:83], v[112:115], v[92:95], v[80:83]
	v_mfma_f32_16x16x32_bf16 v[84:87], v[120:123], v[60:63], v[84:87]
	v_mfma_f32_16x16x32_bf16 v[88:91], v[120:123], v[92:95], v[88:91]
	v_mfma_f32_16x16x32_bf16 v[18:21], v[128:131], v[60:63], v[18:21]
	v_mfma_f32_16x16x32_bf16 v[22:25], v[128:131], v[92:95], v[22:25]
	s_setprio 0
	s_barrier
	s_mov_b32 m0, s42
	v_lshl_add_u64 v[136:137], v[136:137], 0, s[0:1]
	ds_read_b128 v[56:59], v16
	ds_read_b128 v[60:63], v16 offset:1024
	ds_read_b128 v[64:67], v16 offset:2048
	ds_read_b128 v[92:95], v16 offset:3072
	global_load_lds_dwordx4 v[136:137], off
	v_lshl_add_u64 v[136:137], v[138:139], 0, s[0:1]
	s_mov_b32 m0, s43
	s_nop 0
	global_load_lds_dwordx4 v[136:137], off
	s_barrier
	s_waitcnt lgkmcnt(0)
	s_setprio 1
	s_waitcnt lgkmcnt(0)
	v_mfma_f32_16x16x32_bf16 v[100:103], v[96:99], v[56:59], v[100:103]
	v_mfma_f32_16x16x32_bf16 v[36:39], v[96:99], v[64:67], v[36:39]
	v_mfma_f32_16x16x32_bf16 v[40:43], v[108:111], v[56:59], v[40:43]
	v_mfma_f32_16x16x32_bf16 v[44:47], v[108:111], v[64:67], v[44:47]
	v_mfma_f32_16x16x32_bf16 v[48:51], v[116:119], v[56:59], v[48:51]
	v_mfma_f32_16x16x32_bf16 v[52:55], v[116:119], v[64:67], v[52:55]
	v_mfma_f32_16x16x32_bf16 v[26:29], v[124:127], v[56:59], v[26:29]
	v_mfma_f32_16x16x32_bf16 v[30:33], v[124:127], v[64:67], v[30:33]
	v_mfma_f32_16x16x32_bf16 v[100:103], v[104:107], v[60:63], v[100:103]
	v_mfma_f32_16x16x32_bf16 v[36:39], v[104:107], v[92:95], v[36:39]
	v_mfma_f32_16x16x32_bf16 v[40:43], v[112:115], v[60:63], v[40:43]
	v_mfma_f32_16x16x32_bf16 v[44:47], v[112:115], v[92:95], v[44:47]
	v_mfma_f32_16x16x32_bf16 v[48:51], v[120:123], v[60:63], v[48:51]
	v_mfma_f32_16x16x32_bf16 v[52:55], v[120:123], v[92:95], v[52:55]
	v_mfma_f32_16x16x32_bf16 v[26:29], v[128:131], v[60:63], v[26:29]
	v_mfma_f32_16x16x32_bf16 v[30:33], v[128:131], v[92:95], v[30:33]
	s_setprio 0
	s_mov_b32 m0, s29
	v_lshl_add_u64 v[56:57], v[140:141], 0, s[0:1]
	s_barrier
	global_load_lds_dwordx4 v[56:57], off
	v_lshl_add_u64 v[56:57], v[142:143], 0, s[0:1]
	s_mov_b32 m0, s30
	s_nop 0
	global_load_lds_dwordx4 v[56:57], off
	s_barrier
	s_waitcnt lgkmcnt(0)
	s_setprio 1
	s_setprio 0
	s_barrier
	s_add_u32 s16, s10, 0x160080
	s_addc_u32 s17, s11, 0
	s_mov_b32 m0, s44
	v_lshl_add_u64 v[56:57], s[16:17], 0, v[132:133]
	global_load_lds_dwordx4 v[56:57], off
	v_lshl_add_u64 v[56:57], s[16:17], 0, v[134:135]
	s_mov_b32 m0, s45
	s_nop 0
	global_load_lds_dwordx4 v[56:57], off
	s_waitcnt vmcnt(6)
	s_barrier
	s_setprio 1
	s_setprio 0
	v_lshl_or_b32 v2, s27, 8, v1
	v_lshlrev_b64 v[56:57], 2, v[2:3]
	v_lshl_add_u64 v[58:59], v[4:5], 0, v[56:57]
	s_barrier
	s_mov_b64 s[98:99], 0x2000
	s_mov_b64 s[100:101], 0x1a000
	v_mbcnt_lo_u32_b32 v60, -1, 0
	v_mbcnt_hi_u32_b32 v60, -1, v60
	v_and_b32_e32 v61, 15, v60
	v_lshrrev_b32_e32 v60, 4, v60
	v_lshlrev_b32_e32 v60, 2, v60
	v_sub_u32_e32 v60, v60, v61
	v_mul_i32_i24_e32 v60, 0x1ffc, v60
	v_ashrrev_i32_e32 v61, 31, v60
	v_lshl_add_u64 v[58:59], v[60:61], 0, v[58:59]
	global_atomic_add_f32 v[58:59], v68, off
	global_atomic_add_f32 v[58:59], v72, off offset:64
	global_atomic_add_f32 v[58:59], v100, off offset:512
	global_atomic_add_f32 v[58:59], v36, off offset:576
	v_lshl_add_u64 v[60:61], v[58:59], 0, s[98:99]
	global_atomic_add_f32 v[60:61], v69, off
	global_atomic_add_f32 v[60:61], v73, off offset:64
	global_atomic_add_f32 v[60:61], v101, off offset:512
	global_atomic_add_f32 v[60:61], v37, off offset:576
	v_lshl_add_u64 v[58:59], v[60:61], 0, s[98:99]
	global_atomic_add_f32 v[58:59], v70, off
	global_atomic_add_f32 v[58:59], v74, off offset:64
	global_atomic_add_f32 v[58:59], v102, off offset:512
	global_atomic_add_f32 v[58:59], v38, off offset:576
	v_lshl_add_u64 v[60:61], v[58:59], 0, s[98:99]
	global_atomic_add_f32 v[60:61], v71, off
	global_atomic_add_f32 v[60:61], v75, off offset:64
	global_atomic_add_f32 v[60:61], v103, off offset:512
	global_atomic_add_f32 v[60:61], v39, off offset:576
	v_lshl_add_u64 v[58:59], v[60:61], 0, s[100:101]
	global_atomic_add_f32 v[58:59], v76, off
	global_atomic_add_f32 v[58:59], v80, off offset:64
	global_atomic_add_f32 v[58:59], v40, off offset:512
	global_atomic_add_f32 v[58:59], v44, off offset:576
	v_lshl_add_u64 v[60:61], v[58:59], 0, s[98:99]
	global_atomic_add_f32 v[60:61], v77, off
	global_atomic_add_f32 v[60:61], v81, off offset:64
	global_atomic_add_f32 v[60:61], v41, off offset:512
	global_atomic_add_f32 v[60:61], v45, off offset:576
	v_lshl_add_u64 v[58:59], v[60:61], 0, s[98:99]
	global_atomic_add_f32 v[58:59], v78, off
	global_atomic_add_f32 v[58:59], v82, off offset:64
	global_atomic_add_f32 v[58:59], v42, off offset:512
	global_atomic_add_f32 v[58:59], v46, off offset:576
	v_lshl_add_u64 v[60:61], v[58:59], 0, s[98:99]
	global_atomic_add_f32 v[60:61], v79, off
	global_atomic_add_f32 v[60:61], v83, off offset:64
	global_atomic_add_f32 v[60:61], v43, off offset:512
	global_atomic_add_f32 v[60:61], v47, off offset:576
	v_lshl_add_u64 v[58:59], v[60:61], 0, s[100:101]
	global_atomic_add_f32 v[58:59], v84, off
	global_atomic_add_f32 v[58:59], v88, off offset:64
	global_atomic_add_f32 v[58:59], v48, off offset:512
	global_atomic_add_f32 v[58:59], v52, off offset:576
	v_lshl_add_u64 v[60:61], v[58:59], 0, s[98:99]
	global_atomic_add_f32 v[60:61], v85, off
	global_atomic_add_f32 v[60:61], v89, off offset:64
	global_atomic_add_f32 v[60:61], v49, off offset:512
	global_atomic_add_f32 v[60:61], v53, off offset:576
	v_lshl_add_u64 v[58:59], v[60:61], 0, s[98:99]
	global_atomic_add_f32 v[58:59], v86, off
	global_atomic_add_f32 v[58:59], v90, off offset:64
	global_atomic_add_f32 v[58:59], v50, off offset:512
	global_atomic_add_f32 v[58:59], v54, off offset:576
	v_lshl_add_u64 v[60:61], v[58:59], 0, s[98:99]
	global_atomic_add_f32 v[60:61], v87, off
	global_atomic_add_f32 v[60:61], v91, off offset:64
	global_atomic_add_f32 v[60:61], v51, off offset:512
	global_atomic_add_f32 v[60:61], v55, off offset:576
	v_lshl_add_u64 v[58:59], v[60:61], 0, s[100:101]
	global_atomic_add_f32 v[58:59], v18, off
	global_atomic_add_f32 v[58:59], v22, off offset:64
	global_atomic_add_f32 v[58:59], v26, off offset:512
	global_atomic_add_f32 v[58:59], v30, off offset:576
	v_lshl_add_u64 v[60:61], v[58:59], 0, s[98:99]
	global_atomic_add_f32 v[60:61], v19, off
	global_atomic_add_f32 v[60:61], v23, off offset:64
	global_atomic_add_f32 v[60:61], v27, off offset:512
	global_atomic_add_f32 v[60:61], v31, off offset:576
	v_lshl_add_u64 v[58:59], v[60:61], 0, s[98:99]
	global_atomic_add_f32 v[58:59], v20, off
	global_atomic_add_f32 v[58:59], v24, off offset:64
	global_atomic_add_f32 v[58:59], v28, off offset:512
	global_atomic_add_f32 v[58:59], v32, off offset:576
	v_lshl_add_u64 v[60:61], v[58:59], 0, s[98:99]
	global_atomic_add_f32 v[60:61], v21, off
	global_atomic_add_f32 v[60:61], v25, off offset:64
	global_atomic_add_f32 v[60:61], v29, off offset:512
	global_atomic_add_f32 v[60:61], v33, off offset:576
	s_add_i32 s31, s31, s33
	s_andn2_b64 vcc, exec, s[12:13]
	s_mov_b32 s27, s48
	s_mov_b64 s[18:19], s[10:11]
	s_mov_b64 s[16:17], s[14:15]
	s_cbranch_vccz .LBB0_2614

	.amdhsa_kernel _Z10fwd_kernel6Params
		.amdhsa_group_segment_fixed_size 0
		.amdhsa_private_segment_fixed_size 0
		.amdhsa_kernarg_size 568
		.amdhsa_user_sgpr_count 2
		.amdhsa_user_sgpr_dispatch_ptr 0
		.amdhsa_user_sgpr_queue_ptr 0
		.amdhsa_user_sgpr_kernarg_segment_ptr 1
		.amdhsa_user_sgpr_dispatch_id 0
		.amdhsa_user_sgpr_kernarg_preload_length 0
		.amdhsa_user_sgpr_kernarg_preload_offset 0
		.amdhsa_user_sgpr_private_segment_size 0
		.amdhsa_uses_dynamic_stack 0
		.amdhsa_enable_private_segment 0
		.amdhsa_system_sgpr_workgroup_id_x 1
		.amdhsa_system_sgpr_workgroup_id_y 0
		.amdhsa_system_sgpr_workgroup_id_z 0
		.amdhsa_system_sgpr_workgroup_info 0
		.amdhsa_system_vgpr_workitem_id 2
		.amdhsa_next_free_vgpr 256
		.amdhsa_next_free_sgpr 102
		.amdhsa_accum_offset 256
		.amdhsa_reserve_vcc 1
		.amdhsa_float_round_mode_32 0
		.amdhsa_float_round_mode_16_64 0
		.amdhsa_float_denorm_mode_32 3
		.amdhsa_float_denorm_mode_16_64 3
		.amdhsa_dx10_clamp 1
		.amdhsa_ieee_mode 1
		.amdhsa_fp16_overflow 0
		.amdhsa_tg_split 0
		.amdhsa_exception_fp_ieee_invalid_op 0
		.amdhsa_exception_fp_denorm_src 0
		.amdhsa_exception_fp_ieee_div_zero 0
		.amdhsa_exception_fp_ieee_overflow 0
		.amdhsa_exception_fp_ieee_underflow 0
		.amdhsa_exception_fp_ieee_inexact 0
		.amdhsa_exception_int_div_zero 0
	.end_amdhsa_kernel

amdhsa.kernels:
  - .agpr_count:     0
    .args:
      - .offset:         0
        .size:           312
        .value_kind:     by_value
      - .offset:         312
        .size:           4
        .value_kind:     hidden_block_count_x
      - .offset:         316
        .size:           4
        .value_kind:     hidden_block_count_y
      - .offset:         320
        .size:           4
        .value_kind:     hidden_block_count_z
      - .offset:         324
        .size:           2
        .value_kind:     hidden_group_size_x
      - .offset:         326
        .size:           2
        .value_kind:     hidden_group_size_y
      - .offset:         328
        .size:           2
        .value_kind:     hidden_group_size_z
      - .offset:         330
        .size:           2
        .value_kind:     hidden_remainder_x
      - .offset:         332
        .size:           2
        .value_kind:     hidden_remainder_y
      - .offset:         334
        .size:           2
        .value_kind:     hidden_remainder_z
      - .offset:         352
        .size:           8
        .value_kind:     hidden_global_offset_x
      - .offset:         360
        .size:           8
        .value_kind:     hidden_global_offset_y
      - .offset:         368
        .size:           8
        .value_kind:     hidden_global_offset_z
      - .offset:         376
        .size:           2
        .value_kind:     hidden_grid_dims
      - .offset:         400
        .size:           8
        .value_kind:     hidden_multigrid_sync_arg
      - .offset:         432
        .size:           4
        .value_kind:     hidden_dynamic_lds_size
    .group_segment_fixed_size: 0
    .kernarg_segment_align: 8
    .kernarg_segment_size: 568
    .language:       OpenCL C
    .language_version:
      - 2
      - 0
    .max_flat_workgroup_size: 512
    .name:           _Z10fwd_kernel6Params
    .private_segment_fixed_size: 0
    .sgpr_count:     108
    .sgpr_spill_count: 68
    .symbol:         _Z10fwd_kernel6Params.kd
    .uniform_work_group_size: 1
    .uses_dynamic_stack: false
    .vgpr_count:     256
    .vgpr_spill_count: 0
    .wavefront_size: 64
